# GEMM K-loops: removed the repeated lgkmcnt(0) after each barrier and the mid-segment setprio 0/1 pair (fewer issue slots in the MFMA segments)
# baseline (speedup 1.0000x reference)
.LBB0_196:
	s_add_u32 s12, s40, 0xfff00080
	s_addc_u32 s13, s41, -1
	s_add_i32 s76, 0, 0x10000
	s_cmp_eq_u32 s75, 60
	s_cselect_b32 s43, s10, s13
	s_cselect_b32 s42, s11, s12
	s_cselect_b32 s25, s63, s74
	s_cselect_b32 s24, s72, s73
	s_add_i32 s12, 0, 0x14000
	v_add_u32_e32 v140, s76, v223
	v_add_u32_e32 v156, s12, v223
	ds_read_b128 v[128:131], v140
	ds_read_b128 v[132:135], v140 offset:1024
	ds_read_b128 v[136:139], v140 offset:2048
	ds_read_b128 v[140:143], v140 offset:3072
	ds_read_b128 v[144:147], v156
	ds_read_b128 v[148:151], v156 offset:1024
	ds_read_b128 v[152:155], v156 offset:2048
	ds_read_b128 v[156:159], v156 offset:3072
	v_lshl_add_u64 v[194:195], s[40:41], 0, v[206:207]
	s_add_i32 m0, s4, 0xc000
	ds_read_b128 v[160:163], v224
	ds_read_b128 v[164:167], v224 offset:1024
	ds_read_b128 v[168:171], v224 offset:2048
	ds_read_b128 v[172:175], v224 offset:3072
	ds_read_b128 v[176:179], v224 offset:4096
	ds_read_b128 v[180:183], v224 offset:5120
	ds_read_b128 v[184:187], v224 offset:6144
	ds_read_b128 v[188:191], v224 offset:7168
	global_load_lds_dwordx4 v[194:195], off
	v_lshl_add_u64 v[194:195], s[40:41], 0, v[208:209]
	s_add_i32 m0, s4, 0xe000
	s_nop 0
	global_load_lds_dwordx4 v[194:195], off
	s_waitcnt vmcnt(8)
	s_waitcnt lgkmcnt(0)
	s_barrier
	s_setprio 1
	v_mfma_f32_16x16x32_bf16 v[124:127], v[128:131], v[160:163], v[124:127]
	v_mfma_f32_16x16x32_bf16 v[120:123], v[136:139], v[160:163], v[120:123]
	v_mfma_f32_16x16x32_bf16 v[108:111], v[128:131], v[168:171], v[108:111]
	v_mfma_f32_16x16x32_bf16 v[104:107], v[136:139], v[168:171], v[104:107]
	v_mfma_f32_16x16x32_bf16 v[92:95], v[128:131], v[176:179], v[92:95]
	v_mfma_f32_16x16x32_bf16 v[88:91], v[136:139], v[176:179], v[88:91]
	v_mfma_f32_16x16x32_bf16 v[76:79], v[128:131], v[184:187], v[76:79]
	v_mfma_f32_16x16x32_bf16 v[72:75], v[136:139], v[184:187], v[72:75]
	v_mfma_f32_16x16x32_bf16 v[124:127], v[132:135], v[164:167], v[124:127]
	v_mfma_f32_16x16x32_bf16 v[120:123], v[140:143], v[164:167], v[120:123]
	v_mfma_f32_16x16x32_bf16 v[108:111], v[132:135], v[172:175], v[108:111]
	v_mfma_f32_16x16x32_bf16 v[104:107], v[140:143], v[172:175], v[104:107]
	v_mfma_f32_16x16x32_bf16 v[92:95], v[132:135], v[180:183], v[92:95]
	v_mfma_f32_16x16x32_bf16 v[88:91], v[140:143], v[180:183], v[88:91]
	v_mfma_f32_16x16x32_bf16 v[76:79], v[132:135], v[188:191], v[76:79]
	v_mfma_f32_16x16x32_bf16 v[72:75], v[140:143], v[188:191], v[72:75]
	v_mfma_f32_16x16x32_bf16 v[116:119], v[144:147], v[160:163], v[116:119]
	v_mfma_f32_16x16x32_bf16 v[112:115], v[152:155], v[160:163], v[112:115]
	v_mfma_f32_16x16x32_bf16 v[100:103], v[144:147], v[168:171], v[100:103]
	v_mfma_f32_16x16x32_bf16 v[96:99], v[152:155], v[168:171], v[96:99]
	v_mfma_f32_16x16x32_bf16 v[84:87], v[144:147], v[176:179], v[84:87]
	v_mfma_f32_16x16x32_bf16 v[80:83], v[152:155], v[176:179], v[80:83]
	v_mfma_f32_16x16x32_bf16 v[68:71], v[144:147], v[184:187], v[68:71]
	v_mfma_f32_16x16x32_bf16 v[64:67], v[152:155], v[184:187], v[64:67]
	v_mfma_f32_16x16x32_bf16 v[116:119], v[148:151], v[164:167], v[116:119]
	v_mfma_f32_16x16x32_bf16 v[112:115], v[156:159], v[164:167], v[112:115]
	v_mfma_f32_16x16x32_bf16 v[100:103], v[148:151], v[172:175], v[100:103]
	v_mfma_f32_16x16x32_bf16 v[96:99], v[156:159], v[172:175], v[96:99]
	v_mfma_f32_16x16x32_bf16 v[84:87], v[148:151], v[180:183], v[84:87]
	v_mfma_f32_16x16x32_bf16 v[80:83], v[156:159], v[180:183], v[80:83]
	v_mfma_f32_16x16x32_bf16 v[68:71], v[148:151], v[188:191], v[68:71]
	v_mfma_f32_16x16x32_bf16 v[64:67], v[156:159], v[188:191], v[64:67]
	s_setprio 0
	s_barrier
	s_add_i32 s13, s76, s0
	v_lshl_add_u64 v[194:195], s[24:25], 0, v[202:203]
	s_mov_b32 m0, s13
	ds_read_b128 v[160:163], v224 offset:16384
	ds_read_b128 v[164:167], v224 offset:17408
	ds_read_b128 v[168:171], v224 offset:18432
	ds_read_b128 v[172:175], v224 offset:19456
	ds_read_b128 v[176:179], v224 offset:20480
	ds_read_b128 v[180:183], v224 offset:21504
	ds_read_b128 v[184:187], v224 offset:22528
	ds_read_b128 v[188:191], v224 offset:23552
	global_load_lds_dwordx4 v[194:195], off
	s_add_i32 m0, s13, 0x2000
	s_add_u32 s76, s24, 0x100000
	v_lshl_add_u64 v[196:197], s[24:25], 0, v[198:199]
	s_addc_u32 s77, s25, 0
	s_add_i32 s12, s12, s0
	global_load_lds_dwordx4 v[196:197], off
	v_lshl_add_u64 v[210:211], s[76:77], 0, v[202:203]
	s_mov_b32 m0, s12
	v_lshl_add_u64 v[212:213], s[42:43], 0, v[200:201]
	global_load_lds_dwordx4 v[210:211], off
	v_lshl_add_u64 v[210:211], s[76:77], 0, v[198:199]
	s_add_i32 m0, s12, 0x2000
	s_nop 0
	global_load_lds_dwordx4 v[210:211], off
	v_lshl_add_u64 v[210:211], s[42:43], 0, v[204:205]
	s_mov_b32 m0, s4
	s_nop 0
	global_load_lds_dwordx4 v[210:211], off
	s_mov_b32 m0, s5
	s_nop 0
	global_load_lds_dwordx4 v[212:213], off
	s_waitcnt vmcnt(8)
	s_waitcnt lgkmcnt(0)
	s_barrier
	s_setprio 1
	v_mfma_f32_16x16x32_bf16 v[60:63], v[128:131], v[160:163], v[60:63]
	v_mfma_f32_16x16x32_bf16 v[56:59], v[136:139], v[160:163], v[56:59]
	v_mfma_f32_16x16x32_bf16 v[44:47], v[128:131], v[168:171], v[44:47]
	v_mfma_f32_16x16x32_bf16 v[40:43], v[136:139], v[168:171], v[40:43]
	v_mfma_f32_16x16x32_bf16 v[28:31], v[128:131], v[176:179], v[28:31]
	v_mfma_f32_16x16x32_bf16 v[24:27], v[136:139], v[176:179], v[24:27]
	v_mfma_f32_16x16x32_bf16 v[12:15], v[128:131], v[184:187], v[12:15]
	v_mfma_f32_16x16x32_bf16 v[8:11], v[136:139], v[184:187], v[8:11]
	v_mfma_f32_16x16x32_bf16 v[60:63], v[132:135], v[164:167], v[60:63]
	v_mfma_f32_16x16x32_bf16 v[56:59], v[140:143], v[164:167], v[56:59]
	v_mfma_f32_16x16x32_bf16 v[44:47], v[132:135], v[172:175], v[44:47]
	v_mfma_f32_16x16x32_bf16 v[40:43], v[140:143], v[172:175], v[40:43]
	v_mfma_f32_16x16x32_bf16 v[28:31], v[132:135], v[180:183], v[28:31]
	v_mfma_f32_16x16x32_bf16 v[24:27], v[140:143], v[180:183], v[24:27]
	v_mfma_f32_16x16x32_bf16 v[12:15], v[132:135], v[188:191], v[12:15]
	v_mfma_f32_16x16x32_bf16 v[8:11], v[140:143], v[188:191], v[8:11]
	v_mfma_f32_16x16x32_bf16 v[52:55], v[144:147], v[160:163], v[52:55]
	v_mfma_f32_16x16x32_bf16 v[48:51], v[152:155], v[160:163], v[48:51]
	v_mfma_f32_16x16x32_bf16 v[36:39], v[144:147], v[168:171], v[36:39]
	v_mfma_f32_16x16x32_bf16 v[32:35], v[152:155], v[168:171], v[32:35]
	v_mfma_f32_16x16x32_bf16 v[20:23], v[144:147], v[176:179], v[20:23]
	v_mfma_f32_16x16x32_bf16 v[16:19], v[152:155], v[176:179], v[16:19]
	v_mfma_f32_16x16x32_bf16 v[4:7], v[144:147], v[184:187], v[4:7]
	v_mfma_f32_16x16x32_bf16 v[0:3], v[152:155], v[184:187], v[0:3]
	v_mfma_f32_16x16x32_bf16 v[52:55], v[148:151], v[164:167], v[52:55]
	v_mfma_f32_16x16x32_bf16 v[48:51], v[156:159], v[164:167], v[48:51]
	v_mfma_f32_16x16x32_bf16 v[36:39], v[148:151], v[172:175], v[36:39]
	v_mfma_f32_16x16x32_bf16 v[32:35], v[156:159], v[172:175], v[32:35]
	v_mfma_f32_16x16x32_bf16 v[20:23], v[148:151], v[180:183], v[20:23]
	v_mfma_f32_16x16x32_bf16 v[16:19], v[156:159], v[180:183], v[16:19]
	v_mfma_f32_16x16x32_bf16 v[4:7], v[148:151], v[188:191], v[4:7]
	v_mfma_f32_16x16x32_bf16 v[0:3], v[156:159], v[188:191], v[0:3]
	s_setprio 0
	s_barrier
	s_add_i32 s12, 0, 0x18000
	s_add_i32 s13, 0, 0x1c000
	v_add_u32_e32 v140, s12, v223
	v_add_u32_e32 v156, s13, v223
	ds_read_b128 v[128:131], v140
	ds_read_b128 v[132:135], v140 offset:1024
	ds_read_b128 v[136:139], v140 offset:2048
	ds_read_b128 v[140:143], v140 offset:3072
	ds_read_b128 v[144:147], v156
	ds_read_b128 v[148:151], v156 offset:1024
	ds_read_b128 v[152:155], v156 offset:2048
	ds_read_b128 v[156:159], v156 offset:3072
	s_add_u32 s42, s42, 0x100000
	s_addc_u32 s43, s43, 0
	s_mov_b32 m0, s6
	v_lshl_add_u64 v[214:215], s[42:43], 0, v[204:205]
	ds_read_b128 v[160:163], v224 offset:32768
	ds_read_b128 v[164:167], v224 offset:33792
	ds_read_b128 v[168:171], v224 offset:34816
	ds_read_b128 v[172:175], v224 offset:35840
	ds_read_b128 v[176:179], v224 offset:36864
	ds_read_b128 v[180:183], v224 offset:37888
	ds_read_b128 v[184:187], v224 offset:38912
	ds_read_b128 v[188:191], v224 offset:39936
	global_load_lds_dwordx4 v[214:215], off
	v_lshl_add_u64 v[214:215], s[42:43], 0, v[200:201]
	s_mov_b32 m0, s7
	s_nop 0
	global_load_lds_dwordx4 v[214:215], off
	s_waitcnt vmcnt(8)
	s_waitcnt lgkmcnt(0)
	s_barrier
	s_setprio 1
	v_mfma_f32_16x16x32_bf16 v[124:127], v[128:131], v[160:163], v[124:127]
	v_mfma_f32_16x16x32_bf16 v[120:123], v[136:139], v[160:163], v[120:123]
	v_mfma_f32_16x16x32_bf16 v[108:111], v[128:131], v[168:171], v[108:111]
	v_mfma_f32_16x16x32_bf16 v[104:107], v[136:139], v[168:171], v[104:107]
	v_mfma_f32_16x16x32_bf16 v[92:95], v[128:131], v[176:179], v[92:95]
	v_mfma_f32_16x16x32_bf16 v[88:91], v[136:139], v[176:179], v[88:91]
	v_mfma_f32_16x16x32_bf16 v[76:79], v[128:131], v[184:187], v[76:79]
	v_mfma_f32_16x16x32_bf16 v[72:75], v[136:139], v[184:187], v[72:75]
	v_mfma_f32_16x16x32_bf16 v[124:127], v[132:135], v[164:167], v[124:127]
	v_mfma_f32_16x16x32_bf16 v[120:123], v[140:143], v[164:167], v[120:123]
	v_mfma_f32_16x16x32_bf16 v[108:111], v[132:135], v[172:175], v[108:111]
	v_mfma_f32_16x16x32_bf16 v[104:107], v[140:143], v[172:175], v[104:107]
	v_mfma_f32_16x16x32_bf16 v[92:95], v[132:135], v[180:183], v[92:95]
	v_mfma_f32_16x16x32_bf16 v[88:91], v[140:143], v[180:183], v[88:91]
	v_mfma_f32_16x16x32_bf16 v[76:79], v[132:135], v[188:191], v[76:79]
	v_mfma_f32_16x16x32_bf16 v[72:75], v[140:143], v[188:191], v[72:75]
	v_mfma_f32_16x16x32_bf16 v[116:119], v[144:147], v[160:163], v[116:119]
	v_mfma_f32_16x16x32_bf16 v[112:115], v[152:155], v[160:163], v[112:115]
	v_mfma_f32_16x16x32_bf16 v[100:103], v[144:147], v[168:171], v[100:103]
	v_mfma_f32_16x16x32_bf16 v[96:99], v[152:155], v[168:171], v[96:99]
	v_mfma_f32_16x16x32_bf16 v[84:87], v[144:147], v[176:179], v[84:87]
	v_mfma_f32_16x16x32_bf16 v[80:83], v[152:155], v[176:179], v[80:83]
	v_mfma_f32_16x16x32_bf16 v[68:71], v[144:147], v[184:187], v[68:71]
	v_mfma_f32_16x16x32_bf16 v[64:67], v[152:155], v[184:187], v[64:67]
	v_mfma_f32_16x16x32_bf16 v[116:119], v[148:151], v[164:167], v[116:119]
	v_mfma_f32_16x16x32_bf16 v[112:115], v[156:159], v[164:167], v[112:115]
	v_mfma_f32_16x16x32_bf16 v[100:103], v[148:151], v[172:175], v[100:103]
	v_mfma_f32_16x16x32_bf16 v[96:99], v[156:159], v[172:175], v[96:99]
	v_mfma_f32_16x16x32_bf16 v[84:87], v[148:151], v[180:183], v[84:87]
	v_mfma_f32_16x16x32_bf16 v[80:83], v[156:159], v[180:183], v[80:83]
	v_mfma_f32_16x16x32_bf16 v[68:71], v[148:151], v[188:191], v[68:71]
	v_mfma_f32_16x16x32_bf16 v[64:67], v[156:159], v[188:191], v[64:67]
	s_setprio 0
	s_barrier
	s_add_i32 s12, s12, s0
	v_lshl_add_u64 v[194:195], v[194:195], 0, s[34:35]
	s_mov_b32 m0, s12
	ds_read_b128 v[160:163], v224 offset:49152
	ds_read_b128 v[164:167], v224 offset:50176
	ds_read_b128 v[168:171], v224 offset:51200
	ds_read_b128 v[172:175], v224 offset:52224
	ds_read_b128 v[176:179], v224 offset:53248
	ds_read_b128 v[180:183], v224 offset:54272
	ds_read_b128 v[184:187], v224 offset:55296
	ds_read_b128 v[188:191], v224 offset:56320
	global_load_lds_dwordx4 v[194:195], off
	s_add_i32 m0, s12, 0x2000
	s_add_u32 s24, s24, 0x100080
	v_lshl_add_u64 v[194:195], v[196:197], 0, s[34:35]
	s_addc_u32 s25, s25, 0
	s_add_i32 s12, s13, s0
	global_load_lds_dwordx4 v[194:195], off
	v_lshl_add_u64 v[194:195], s[24:25], 0, v[202:203]
	s_mov_b32 m0, s12
	s_nop 0
	global_load_lds_dwordx4 v[194:195], off
	v_lshl_add_u64 v[194:195], s[24:25], 0, v[198:199]
	s_add_i32 m0, s12, 0x2000
	s_nop 0
	global_load_lds_dwordx4 v[194:195], off
	v_lshl_add_u64 v[194:195], v[210:211], 0, s[34:35]
	s_mov_b32 m0, s44
	s_nop 0
	global_load_lds_dwordx4 v[194:195], off
	v_lshl_add_u64 v[194:195], v[212:213], 0, s[34:35]
	s_mov_b32 m0, s45
	s_nop 0
	global_load_lds_dwordx4 v[194:195], off
	s_waitcnt vmcnt(8)
	s_waitcnt lgkmcnt(0)
	s_barrier
	s_setprio 1
	v_mfma_f32_16x16x32_bf16 v[60:63], v[128:131], v[160:163], v[60:63]
	v_mfma_f32_16x16x32_bf16 v[56:59], v[136:139], v[160:163], v[56:59]
	v_mfma_f32_16x16x32_bf16 v[44:47], v[128:131], v[168:171], v[44:47]
	v_mfma_f32_16x16x32_bf16 v[40:43], v[136:139], v[168:171], v[40:43]
	v_mfma_f32_16x16x32_bf16 v[28:31], v[128:131], v[176:179], v[28:31]
	v_mfma_f32_16x16x32_bf16 v[24:27], v[136:139], v[176:179], v[24:27]
	v_mfma_f32_16x16x32_bf16 v[12:15], v[128:131], v[184:187], v[12:15]
	v_mfma_f32_16x16x32_bf16 v[8:11], v[136:139], v[184:187], v[8:11]
	v_mfma_f32_16x16x32_bf16 v[60:63], v[132:135], v[164:167], v[60:63]
	v_mfma_f32_16x16x32_bf16 v[56:59], v[140:143], v[164:167], v[56:59]
	v_mfma_f32_16x16x32_bf16 v[44:47], v[132:135], v[172:175], v[44:47]
	v_mfma_f32_16x16x32_bf16 v[40:43], v[140:143], v[172:175], v[40:43]
	v_mfma_f32_16x16x32_bf16 v[28:31], v[132:135], v[180:183], v[28:31]
	v_mfma_f32_16x16x32_bf16 v[24:27], v[140:143], v[180:183], v[24:27]
	v_mfma_f32_16x16x32_bf16 v[12:15], v[132:135], v[188:191], v[12:15]
	v_mfma_f32_16x16x32_bf16 v[8:11], v[140:143], v[188:191], v[8:11]
	v_mfma_f32_16x16x32_bf16 v[52:55], v[144:147], v[160:163], v[52:55]
	v_mfma_f32_16x16x32_bf16 v[48:51], v[152:155], v[160:163], v[48:51]
	v_mfma_f32_16x16x32_bf16 v[36:39], v[144:147], v[168:171], v[36:39]
	v_mfma_f32_16x16x32_bf16 v[32:35], v[152:155], v[168:171], v[32:35]
	v_mfma_f32_16x16x32_bf16 v[20:23], v[144:147], v[176:179], v[20:23]
	v_mfma_f32_16x16x32_bf16 v[16:19], v[152:155], v[176:179], v[16:19]
	v_mfma_f32_16x16x32_bf16 v[4:7], v[144:147], v[184:187], v[4:7]
	v_mfma_f32_16x16x32_bf16 v[0:3], v[152:155], v[184:187], v[0:3]
	v_mfma_f32_16x16x32_bf16 v[52:55], v[148:151], v[164:167], v[52:55]
	v_mfma_f32_16x16x32_bf16 v[48:51], v[156:159], v[164:167], v[48:51]
	v_mfma_f32_16x16x32_bf16 v[36:39], v[148:151], v[172:175], v[36:39]
	v_mfma_f32_16x16x32_bf16 v[32:35], v[156:159], v[172:175], v[32:35]
	v_mfma_f32_16x16x32_bf16 v[20:23], v[148:151], v[180:183], v[20:23]
	v_mfma_f32_16x16x32_bf16 v[16:19], v[156:159], v[180:183], v[16:19]
	v_mfma_f32_16x16x32_bf16 v[4:7], v[148:151], v[188:191], v[4:7]
	v_mfma_f32_16x16x32_bf16 v[0:3], v[156:159], v[188:191], v[0:3]
	s_setprio 0
	s_barrier
	s_add_i32 s75, s75, 2
	s_add_u32 s40, s40, 0x100
	s_addc_u32 s41, s41, 0
	s_add_u32 s73, s73, 0x100
	s_addc_u32 s74, s74, 0
	s_cmp_lt_u32 s75, 62
	s_cbranch_scc1 .LBB0_196
	s_andn2_b64 vcc, exec, s[46:47]
	s_cbranch_vccnz .LBB0_199
	s_barrier

.LBB0_461:
	s_add_u32 s12, s56, 0xfff00080
	s_addc_u32 s13, s57, -1
	s_add_i32 s74, 0, 0x10000
	s_cmp_eq_u32 s73, 60
	s_cselect_b32 s61, s47, s13
	s_cselect_b32 s60, s59, s12
	v_add_u32_e32 v138, s74, v140
	s_cselect_b32 s25, s43, s72
	s_cselect_b32 s24, s62, s63
	s_add_i32 s12, 0, 0x14000
	ds_read_b128 v[142:145], v138
	ds_read_b128 v[146:149], v138 offset:1024
	ds_read_b128 v[150:153], v138 offset:2048
	ds_read_b128 v[154:157], v138 offset:3072
	v_add_u32_e32 v138, s12, v140
	ds_read_b128 v[158:161], v138
	ds_read_b128 v[162:165], v138 offset:1024
	ds_read_b128 v[166:169], v138 offset:2048
	ds_read_b128 v[170:173], v138 offset:3072
	v_lshl_add_u64 v[138:139], s[56:57], 0, v[134:135]
	s_add_i32 m0, s4, 0xc000
	ds_read_b128 v[174:177], v141
	ds_read_b128 v[178:181], v141 offset:1024
	ds_read_b128 v[182:185], v141 offset:2048
	ds_read_b128 v[186:189], v141 offset:3072
	ds_read_b128 v[194:197], v141 offset:4096
	ds_read_b128 v[198:201], v141 offset:5120
	ds_read_b128 v[202:205], v141 offset:6144
	ds_read_b128 v[206:209], v141 offset:7168
	global_load_lds_dwordx4 v[138:139], off
	v_lshl_add_u64 v[138:139], s[56:57], 0, v[136:137]
	s_add_i32 m0, s4, 0xe000
	s_nop 0
	global_load_lds_dwordx4 v[138:139], off
	s_waitcnt vmcnt(8)
	s_waitcnt lgkmcnt(0)
	s_barrier
	s_setprio 1
	v_mfma_f32_16x16x32_bf16 v[124:127], v[142:145], v[174:177], v[124:127]
	v_mfma_f32_16x16x32_bf16 v[120:123], v[150:153], v[174:177], v[120:123]
	v_mfma_f32_16x16x32_bf16 v[116:119], v[142:145], v[182:185], v[116:119]
	v_mfma_f32_16x16x32_bf16 v[108:111], v[150:153], v[182:185], v[108:111]
	v_mfma_f32_16x16x32_bf16 v[100:103], v[142:145], v[194:197], v[100:103]
	v_mfma_f32_16x16x32_bf16 v[92:95], v[150:153], v[194:197], v[92:95]
	v_mfma_f32_16x16x32_bf16 v[84:87], v[142:145], v[202:205], v[84:87]
	v_mfma_f32_16x16x32_bf16 v[76:79], v[150:153], v[202:205], v[76:79]
	v_mfma_f32_16x16x32_bf16 v[124:127], v[146:149], v[178:181], v[124:127]
	v_mfma_f32_16x16x32_bf16 v[120:123], v[154:157], v[178:181], v[120:123]
	v_mfma_f32_16x16x32_bf16 v[116:119], v[146:149], v[186:189], v[116:119]
	v_mfma_f32_16x16x32_bf16 v[108:111], v[154:157], v[186:189], v[108:111]
	v_mfma_f32_16x16x32_bf16 v[100:103], v[146:149], v[198:201], v[100:103]
	v_mfma_f32_16x16x32_bf16 v[92:95], v[154:157], v[198:201], v[92:95]
	v_mfma_f32_16x16x32_bf16 v[84:87], v[146:149], v[206:209], v[84:87]
	v_mfma_f32_16x16x32_bf16 v[76:79], v[154:157], v[206:209], v[76:79]
	v_mfma_f32_16x16x32_bf16 v[112:115], v[158:161], v[174:177], v[112:115]
	v_mfma_f32_16x16x32_bf16 v[104:107], v[166:169], v[174:177], v[104:107]
	v_mfma_f32_16x16x32_bf16 v[96:99], v[158:161], v[182:185], v[96:99]
	v_mfma_f32_16x16x32_bf16 v[88:91], v[166:169], v[182:185], v[88:91]
	v_mfma_f32_16x16x32_bf16 v[80:83], v[158:161], v[194:197], v[80:83]
	v_mfma_f32_16x16x32_bf16 v[72:75], v[166:169], v[194:197], v[72:75]
	v_mfma_f32_16x16x32_bf16 v[68:71], v[158:161], v[202:205], v[68:71]
	v_mfma_f32_16x16x32_bf16 v[64:67], v[166:169], v[202:205], v[64:67]
	v_mfma_f32_16x16x32_bf16 v[112:115], v[162:165], v[178:181], v[112:115]
	v_mfma_f32_16x16x32_bf16 v[104:107], v[170:173], v[178:181], v[104:107]
	v_mfma_f32_16x16x32_bf16 v[96:99], v[162:165], v[186:189], v[96:99]
	v_mfma_f32_16x16x32_bf16 v[88:91], v[170:173], v[186:189], v[88:91]
	v_mfma_f32_16x16x32_bf16 v[80:83], v[162:165], v[198:201], v[80:83]
	v_mfma_f32_16x16x32_bf16 v[72:75], v[170:173], v[198:201], v[72:75]
	v_mfma_f32_16x16x32_bf16 v[68:71], v[162:165], v[206:209], v[68:71]
	v_mfma_f32_16x16x32_bf16 v[64:67], v[170:173], v[206:209], v[64:67]
	s_setprio 0
	s_barrier
	s_add_i32 s13, s74, s0
	v_lshl_add_u64 v[138:139], s[24:25], 0, v[192:193]
	s_mov_b32 m0, s13
	ds_read_b128 v[174:177], v141 offset:16384
	ds_read_b128 v[178:181], v141 offset:17408
	ds_read_b128 v[182:185], v141 offset:18432
	ds_read_b128 v[186:189], v141 offset:19456
	ds_read_b128 v[194:197], v141 offset:20480
	ds_read_b128 v[198:201], v141 offset:21504
	ds_read_b128 v[202:205], v141 offset:22528
	ds_read_b128 v[206:209], v141 offset:23552
	global_load_lds_dwordx4 v[138:139], off
	s_add_i32 m0, s13, 0x2000
	s_add_u32 s74, s24, 0x100000
	v_lshl_add_u64 v[190:191], s[24:25], 0, v[128:129]
	s_addc_u32 s75, s25, 0
	s_add_i32 s12, s12, s0
	global_load_lds_dwordx4 v[190:191], off
	v_lshl_add_u64 v[210:211], s[74:75], 0, v[192:193]
	s_mov_b32 m0, s12
	v_lshl_add_u64 v[212:213], s[60:61], 0, v[130:131]
	global_load_lds_dwordx4 v[210:211], off
	v_lshl_add_u64 v[210:211], s[74:75], 0, v[128:129]
	s_add_i32 m0, s12, 0x2000
	s_nop 0
	global_load_lds_dwordx4 v[210:211], off
	v_lshl_add_u64 v[210:211], s[60:61], 0, v[132:133]
	s_mov_b32 m0, s4
	s_nop 0
	global_load_lds_dwordx4 v[210:211], off
	s_mov_b32 m0, s5
	s_nop 0
	global_load_lds_dwordx4 v[212:213], off
	s_waitcnt vmcnt(8)
	s_waitcnt lgkmcnt(0)
	s_barrier
	s_setprio 1
	v_mfma_f32_16x16x32_bf16 v[60:63], v[142:145], v[174:177], v[60:63]
	v_mfma_f32_16x16x32_bf16 v[56:59], v[150:153], v[174:177], v[56:59]
	v_mfma_f32_16x16x32_bf16 v[52:55], v[142:145], v[182:185], v[52:55]
	v_mfma_f32_16x16x32_bf16 v[44:47], v[150:153], v[182:185], v[44:47]
	v_mfma_f32_16x16x32_bf16 v[36:39], v[142:145], v[194:197], v[36:39]
	v_mfma_f32_16x16x32_bf16 v[28:31], v[150:153], v[194:197], v[28:31]
	v_mfma_f32_16x16x32_bf16 v[20:23], v[142:145], v[202:205], v[20:23]
	v_mfma_f32_16x16x32_bf16 v[12:15], v[150:153], v[202:205], v[12:15]
	v_mfma_f32_16x16x32_bf16 v[60:63], v[146:149], v[178:181], v[60:63]
	v_mfma_f32_16x16x32_bf16 v[56:59], v[154:157], v[178:181], v[56:59]
	v_mfma_f32_16x16x32_bf16 v[52:55], v[146:149], v[186:189], v[52:55]
	v_mfma_f32_16x16x32_bf16 v[44:47], v[154:157], v[186:189], v[44:47]
	v_mfma_f32_16x16x32_bf16 v[36:39], v[146:149], v[198:201], v[36:39]
	v_mfma_f32_16x16x32_bf16 v[28:31], v[154:157], v[198:201], v[28:31]
	v_mfma_f32_16x16x32_bf16 v[20:23], v[146:149], v[206:209], v[20:23]
	v_mfma_f32_16x16x32_bf16 v[12:15], v[154:157], v[206:209], v[12:15]
	v_mfma_f32_16x16x32_bf16 v[48:51], v[158:161], v[174:177], v[48:51]
	v_mfma_f32_16x16x32_bf16 v[40:43], v[166:169], v[174:177], v[40:43]
	v_mfma_f32_16x16x32_bf16 v[32:35], v[158:161], v[182:185], v[32:35]
	v_mfma_f32_16x16x32_bf16 v[24:27], v[166:169], v[182:185], v[24:27]
	v_mfma_f32_16x16x32_bf16 v[16:19], v[158:161], v[194:197], v[16:19]
	v_mfma_f32_16x16x32_bf16 v[8:11], v[166:169], v[194:197], v[8:11]
	v_mfma_f32_16x16x32_bf16 v[4:7], v[158:161], v[202:205], v[4:7]
	v_mfma_f32_16x16x32_bf16 v[0:3], v[166:169], v[202:205], v[0:3]
	v_mfma_f32_16x16x32_bf16 v[48:51], v[162:165], v[178:181], v[48:51]
	v_mfma_f32_16x16x32_bf16 v[40:43], v[170:173], v[178:181], v[40:43]
	v_mfma_f32_16x16x32_bf16 v[32:35], v[162:165], v[186:189], v[32:35]
	v_mfma_f32_16x16x32_bf16 v[24:27], v[170:173], v[186:189], v[24:27]
	v_mfma_f32_16x16x32_bf16 v[16:19], v[162:165], v[198:201], v[16:19]
	v_mfma_f32_16x16x32_bf16 v[8:11], v[170:173], v[198:201], v[8:11]
	v_mfma_f32_16x16x32_bf16 v[4:7], v[162:165], v[206:209], v[4:7]
	v_mfma_f32_16x16x32_bf16 v[0:3], v[170:173], v[206:209], v[0:3]
	s_setprio 0
	s_barrier
	s_add_i32 s12, 0, 0x18000
	s_add_i32 s13, 0, 0x1c000
	v_add_u32_e32 v154, s12, v140
	v_add_u32_e32 v170, s13, v140
	ds_read_b128 v[142:145], v154
	ds_read_b128 v[146:149], v154 offset:1024
	ds_read_b128 v[150:153], v154 offset:2048
	ds_read_b128 v[154:157], v154 offset:3072
	ds_read_b128 v[158:161], v170
	ds_read_b128 v[162:165], v170 offset:1024
	ds_read_b128 v[166:169], v170 offset:2048
	ds_read_b128 v[170:173], v170 offset:3072
	s_add_u32 s60, s60, 0x100000
	s_addc_u32 s61, s61, 0
	s_mov_b32 m0, s6
	v_lshl_add_u64 v[214:215], s[60:61], 0, v[132:133]
	ds_read_b128 v[174:177], v141 offset:32768
	ds_read_b128 v[178:181], v141 offset:33792
	ds_read_b128 v[182:185], v141 offset:34816
	ds_read_b128 v[186:189], v141 offset:35840
	ds_read_b128 v[194:197], v141 offset:36864
	ds_read_b128 v[198:201], v141 offset:37888
	ds_read_b128 v[202:205], v141 offset:38912
	ds_read_b128 v[206:209], v141 offset:39936
	global_load_lds_dwordx4 v[214:215], off
	v_lshl_add_u64 v[214:215], s[60:61], 0, v[130:131]
	s_mov_b32 m0, s7
	s_nop 0
	global_load_lds_dwordx4 v[214:215], off
	s_waitcnt vmcnt(8)
	s_waitcnt lgkmcnt(0)
	s_barrier
	s_setprio 1
	v_mfma_f32_16x16x32_bf16 v[124:127], v[142:145], v[174:177], v[124:127]
	v_mfma_f32_16x16x32_bf16 v[120:123], v[150:153], v[174:177], v[120:123]
	v_mfma_f32_16x16x32_bf16 v[116:119], v[142:145], v[182:185], v[116:119]
	v_mfma_f32_16x16x32_bf16 v[108:111], v[150:153], v[182:185], v[108:111]
	v_mfma_f32_16x16x32_bf16 v[100:103], v[142:145], v[194:197], v[100:103]
	v_mfma_f32_16x16x32_bf16 v[92:95], v[150:153], v[194:197], v[92:95]
	v_mfma_f32_16x16x32_bf16 v[84:87], v[142:145], v[202:205], v[84:87]
	v_mfma_f32_16x16x32_bf16 v[76:79], v[150:153], v[202:205], v[76:79]
	v_mfma_f32_16x16x32_bf16 v[124:127], v[146:149], v[178:181], v[124:127]
	v_mfma_f32_16x16x32_bf16 v[120:123], v[154:157], v[178:181], v[120:123]
	v_mfma_f32_16x16x32_bf16 v[116:119], v[146:149], v[186:189], v[116:119]
	v_mfma_f32_16x16x32_bf16 v[108:111], v[154:157], v[186:189], v[108:111]
	v_mfma_f32_16x16x32_bf16 v[100:103], v[146:149], v[198:201], v[100:103]
	v_mfma_f32_16x16x32_bf16 v[92:95], v[154:157], v[198:201], v[92:95]
	v_mfma_f32_16x16x32_bf16 v[84:87], v[146:149], v[206:209], v[84:87]
	v_mfma_f32_16x16x32_bf16 v[76:79], v[154:157], v[206:209], v[76:79]
	v_mfma_f32_16x16x32_bf16 v[112:115], v[158:161], v[174:177], v[112:115]
	v_mfma_f32_16x16x32_bf16 v[104:107], v[166:169], v[174:177], v[104:107]
	v_mfma_f32_16x16x32_bf16 v[96:99], v[158:161], v[182:185], v[96:99]
	v_mfma_f32_16x16x32_bf16 v[88:91], v[166:169], v[182:185], v[88:91]
	v_mfma_f32_16x16x32_bf16 v[80:83], v[158:161], v[194:197], v[80:83]
	v_mfma_f32_16x16x32_bf16 v[72:75], v[166:169], v[194:197], v[72:75]
	v_mfma_f32_16x16x32_bf16 v[68:71], v[158:161], v[202:205], v[68:71]
	v_mfma_f32_16x16x32_bf16 v[64:67], v[166:169], v[202:205], v[64:67]
	v_mfma_f32_16x16x32_bf16 v[112:115], v[162:165], v[178:181], v[112:115]
	v_mfma_f32_16x16x32_bf16 v[104:107], v[170:173], v[178:181], v[104:107]
	v_mfma_f32_16x16x32_bf16 v[96:99], v[162:165], v[186:189], v[96:99]
	v_mfma_f32_16x16x32_bf16 v[88:91], v[170:173], v[186:189], v[88:91]
	v_mfma_f32_16x16x32_bf16 v[80:83], v[162:165], v[198:201], v[80:83]
	v_mfma_f32_16x16x32_bf16 v[72:75], v[170:173], v[198:201], v[72:75]
	v_mfma_f32_16x16x32_bf16 v[68:71], v[162:165], v[206:209], v[68:71]
	v_mfma_f32_16x16x32_bf16 v[64:67], v[170:173], v[206:209], v[64:67]
	s_setprio 0
	s_barrier
	s_add_i32 s12, s12, s0
	v_lshl_add_u64 v[138:139], v[138:139], 0, s[34:35]
	s_mov_b32 m0, s12
	ds_read_b128 v[174:177], v141 offset:49152
	ds_read_b128 v[178:181], v141 offset:50176
	ds_read_b128 v[182:185], v141 offset:51200
	ds_read_b128 v[186:189], v141 offset:52224
	ds_read_b128 v[194:197], v141 offset:53248
	ds_read_b128 v[198:201], v141 offset:54272
	ds_read_b128 v[202:205], v141 offset:55296
	ds_read_b128 v[206:209], v141 offset:56320
	global_load_lds_dwordx4 v[138:139], off
	s_add_i32 m0, s12, 0x2000
	s_add_u32 s24, s24, 0x100080
	v_lshl_add_u64 v[138:139], v[190:191], 0, s[34:35]
	s_addc_u32 s25, s25, 0
	s_add_i32 s12, s13, s0
	global_load_lds_dwordx4 v[138:139], off
	v_lshl_add_u64 v[138:139], s[24:25], 0, v[192:193]
	s_mov_b32 m0, s12
	s_nop 0
	global_load_lds_dwordx4 v[138:139], off
	v_lshl_add_u64 v[138:139], s[24:25], 0, v[128:129]
	s_add_i32 m0, s12, 0x2000
	s_nop 0
	global_load_lds_dwordx4 v[138:139], off
	v_lshl_add_u64 v[138:139], v[210:211], 0, s[34:35]
	s_mov_b32 m0, s10
	s_nop 0
	global_load_lds_dwordx4 v[138:139], off
	v_lshl_add_u64 v[138:139], v[212:213], 0, s[34:35]
	s_mov_b32 m0, s11
	s_nop 0
	global_load_lds_dwordx4 v[138:139], off
	s_waitcnt vmcnt(8)
	s_waitcnt lgkmcnt(0)
	s_barrier
	s_setprio 1
	v_mfma_f32_16x16x32_bf16 v[60:63], v[142:145], v[174:177], v[60:63]
	v_mfma_f32_16x16x32_bf16 v[56:59], v[150:153], v[174:177], v[56:59]
	v_mfma_f32_16x16x32_bf16 v[52:55], v[142:145], v[182:185], v[52:55]
	v_mfma_f32_16x16x32_bf16 v[44:47], v[150:153], v[182:185], v[44:47]
	v_mfma_f32_16x16x32_bf16 v[36:39], v[142:145], v[194:197], v[36:39]
	v_mfma_f32_16x16x32_bf16 v[28:31], v[150:153], v[194:197], v[28:31]
	v_mfma_f32_16x16x32_bf16 v[20:23], v[142:145], v[202:205], v[20:23]
	v_mfma_f32_16x16x32_bf16 v[12:15], v[150:153], v[202:205], v[12:15]
	v_mfma_f32_16x16x32_bf16 v[60:63], v[146:149], v[178:181], v[60:63]
	v_mfma_f32_16x16x32_bf16 v[56:59], v[154:157], v[178:181], v[56:59]
	v_mfma_f32_16x16x32_bf16 v[52:55], v[146:149], v[186:189], v[52:55]
	v_mfma_f32_16x16x32_bf16 v[44:47], v[154:157], v[186:189], v[44:47]
	v_mfma_f32_16x16x32_bf16 v[36:39], v[146:149], v[198:201], v[36:39]
	v_mfma_f32_16x16x32_bf16 v[28:31], v[154:157], v[198:201], v[28:31]
	v_mfma_f32_16x16x32_bf16 v[20:23], v[146:149], v[206:209], v[20:23]
	v_mfma_f32_16x16x32_bf16 v[12:15], v[154:157], v[206:209], v[12:15]
	v_mfma_f32_16x16x32_bf16 v[48:51], v[158:161], v[174:177], v[48:51]
	v_mfma_f32_16x16x32_bf16 v[40:43], v[166:169], v[174:177], v[40:43]
	v_mfma_f32_16x16x32_bf16 v[32:35], v[158:161], v[182:185], v[32:35]
	v_mfma_f32_16x16x32_bf16 v[24:27], v[166:169], v[182:185], v[24:27]
	v_mfma_f32_16x16x32_bf16 v[16:19], v[158:161], v[194:197], v[16:19]
	v_mfma_f32_16x16x32_bf16 v[8:11], v[166:169], v[194:197], v[8:11]
	v_mfma_f32_16x16x32_bf16 v[4:7], v[158:161], v[202:205], v[4:7]
	v_mfma_f32_16x16x32_bf16 v[0:3], v[166:169], v[202:205], v[0:3]
	v_mfma_f32_16x16x32_bf16 v[48:51], v[162:165], v[178:181], v[48:51]
	v_mfma_f32_16x16x32_bf16 v[40:43], v[170:173], v[178:181], v[40:43]
	v_mfma_f32_16x16x32_bf16 v[32:35], v[162:165], v[186:189], v[32:35]
	v_mfma_f32_16x16x32_bf16 v[24:27], v[170:173], v[186:189], v[24:27]
	v_mfma_f32_16x16x32_bf16 v[16:19], v[162:165], v[198:201], v[16:19]
	v_mfma_f32_16x16x32_bf16 v[8:11], v[170:173], v[198:201], v[8:11]
	v_mfma_f32_16x16x32_bf16 v[4:7], v[162:165], v[206:209], v[4:7]
	v_mfma_f32_16x16x32_bf16 v[0:3], v[170:173], v[206:209], v[0:3]
	s_setprio 0
	s_barrier
	s_add_i32 s73, s73, 2
	s_add_u32 s56, s56, 0x100
	s_addc_u32 s57, s57, 0
	s_add_u32 s63, s63, 0x100
	s_addc_u32 s72, s72, 0
	s_cmp_lt_u32 s73, 62
	s_cbranch_scc1 .LBB0_461
	s_andn2_b64 vcc, exec, s[38:39]
	s_cbranch_vccnz .LBB0_464
	s_barrier

.LBB0_552:
	s_add_u32 s12, s50, 0xfff80080
	s_addc_u32 s13, s51, -1
	s_add_i32 s44, 0, 0x10000
	s_cmp_eq_u32 s29, 28
	s_cselect_b32 s53, s6, s13
	s_cselect_b32 s52, s7, s12
	s_cselect_b32 s25, s8, s11
	s_cselect_b32 s24, s9, s10
	s_add_i32 s12, 0, 0x14000
	s_waitcnt vmcnt(0)
	v_add_u32_e32 v60, s44, v198
	v_add_u32_e32 v166, s12, v198
	ds_read_b128 v[20:23], v60
	ds_read_b128 v[32:35], v60 offset:1024
	ds_read_b128 v[56:59], v60 offset:2048
	ds_read_b128 v[60:63], v60 offset:3072
	ds_read_b128 v[154:157], v166
	ds_read_b128 v[158:161], v166 offset:1024
	ds_read_b128 v[162:165], v166 offset:2048
	ds_read_b128 v[166:169], v166 offset:3072
	v_lshl_add_u64 v[190:191], s[50:51], 0, v[150:151]
	s_add_i32 m0, s56, 0xc000
	ds_read_b128 v[170:173], v199
	ds_read_b128 v[174:177], v199 offset:1024
	ds_read_b128 v[178:181], v199 offset:2048
	ds_read_b128 v[182:185], v199 offset:3072
	ds_read_b128 v[186:189], v199 offset:4096
	ds_read_b128 v[194:197], v199 offset:5120
	ds_read_b128 v[200:203], v199 offset:6144
	ds_read_b128 v[204:207], v199 offset:7168
	global_load_lds_dwordx4 v[190:191], off
	v_lshl_add_u64 v[190:191], s[50:51], 0, v[152:153]
	s_add_i32 m0, s56, 0xe000
	s_nop 0
	global_load_lds_dwordx4 v[190:191], off
	s_waitcnt vmcnt(8)
	s_waitcnt lgkmcnt(0)
	s_barrier
	s_setprio 1
	v_mfma_i32_16x16x64_i8 v[140:143], v[20:23], v[170:173], v[140:143]
	v_mfma_i32_16x16x64_i8 v[136:139], v[56:59], v[170:173], v[136:139]
	v_mfma_i32_16x16x64_i8 v[132:135], v[20:23], v[178:181], v[132:135]
	v_mfma_i32_16x16x64_i8 v[124:127], v[56:59], v[178:181], v[124:127]
	v_mfma_i32_16x16x64_i8 v[116:119], v[20:23], v[186:189], v[116:119]
	v_mfma_i32_16x16x64_i8 v[108:111], v[56:59], v[186:189], v[108:111]
	v_mfma_i32_16x16x64_i8 v[100:103], v[20:23], v[200:203], v[100:103]
	v_mfma_i32_16x16x64_i8 v[92:95], v[56:59], v[200:203], v[92:95]
	v_mfma_i32_16x16x64_i8 v[140:143], v[32:35], v[174:177], v[140:143]
	v_mfma_i32_16x16x64_i8 v[136:139], v[60:63], v[174:177], v[136:139]
	v_mfma_i32_16x16x64_i8 v[132:135], v[32:35], v[182:185], v[132:135]
	v_mfma_i32_16x16x64_i8 v[124:127], v[60:63], v[182:185], v[124:127]
	v_mfma_i32_16x16x64_i8 v[116:119], v[32:35], v[194:197], v[116:119]
	v_mfma_i32_16x16x64_i8 v[108:111], v[60:63], v[194:197], v[108:111]
	v_mfma_i32_16x16x64_i8 v[100:103], v[32:35], v[204:207], v[100:103]
	v_mfma_i32_16x16x64_i8 v[92:95], v[60:63], v[204:207], v[92:95]
	v_mfma_i32_16x16x64_i8 v[128:131], v[154:157], v[170:173], v[128:131]
	v_mfma_i32_16x16x64_i8 v[120:123], v[162:165], v[170:173], v[120:123]
	v_mfma_i32_16x16x64_i8 v[112:115], v[154:157], v[178:181], v[112:115]
	v_mfma_i32_16x16x64_i8 v[104:107], v[162:165], v[178:181], v[104:107]
	v_mfma_i32_16x16x64_i8 v[96:99], v[154:157], v[186:189], v[96:99]
	v_mfma_i32_16x16x64_i8 v[88:91], v[162:165], v[186:189], v[88:91]
	v_mfma_i32_16x16x64_i8 v[84:87], v[154:157], v[200:203], v[84:87]
	v_mfma_i32_16x16x64_i8 v[80:83], v[162:165], v[200:203], v[80:83]
	v_mfma_i32_16x16x64_i8 v[128:131], v[158:161], v[174:177], v[128:131]
	v_mfma_i32_16x16x64_i8 v[120:123], v[166:169], v[174:177], v[120:123]
	v_mfma_i32_16x16x64_i8 v[112:115], v[158:161], v[182:185], v[112:115]
	v_mfma_i32_16x16x64_i8 v[104:107], v[166:169], v[182:185], v[104:107]
	v_mfma_i32_16x16x64_i8 v[96:99], v[158:161], v[194:197], v[96:99]
	v_mfma_i32_16x16x64_i8 v[88:91], v[166:169], v[194:197], v[88:91]
	v_mfma_i32_16x16x64_i8 v[84:87], v[158:161], v[204:207], v[84:87]
	v_mfma_i32_16x16x64_i8 v[80:83], v[166:169], v[204:207], v[80:83]
	s_setprio 0
	s_barrier
	s_add_i32 s13, s44, s0
	v_lshl_add_u64 v[190:191], s[24:25], 0, v[192:193]
	s_mov_b32 m0, s13
	ds_read_b128 v[170:173], v199 offset:16384
	ds_read_b128 v[174:177], v199 offset:17408
	ds_read_b128 v[178:181], v199 offset:18432
	ds_read_b128 v[182:185], v199 offset:19456
	ds_read_b128 v[186:189], v199 offset:20480
	ds_read_b128 v[194:197], v199 offset:21504
	ds_read_b128 v[200:203], v199 offset:22528
	ds_read_b128 v[204:207], v199 offset:23552
	global_load_lds_dwordx4 v[190:191], off
	s_add_i32 m0, s13, 0x2000
	s_add_u32 s44, s24, 0x80000
	v_lshl_add_u64 v[208:209], s[24:25], 0, v[144:145]
	s_addc_u32 s45, s25, 0
	s_add_i32 s12, s12, s0
	global_load_lds_dwordx4 v[208:209], off
	v_lshl_add_u64 v[210:211], s[44:45], 0, v[192:193]
	s_mov_b32 m0, s12
	v_lshl_add_u64 v[212:213], s[52:53], 0, v[146:147]
	global_load_lds_dwordx4 v[210:211], off
	v_lshl_add_u64 v[210:211], s[44:45], 0, v[144:145]
	s_add_i32 m0, s12, 0x2000
	s_nop 0
	global_load_lds_dwordx4 v[210:211], off
	v_lshl_add_u64 v[210:211], s[52:53], 0, v[148:149]
	s_mov_b32 m0, s56
	s_nop 0
	global_load_lds_dwordx4 v[210:211], off
	s_mov_b32 m0, s57
	s_nop 0
	global_load_lds_dwordx4 v[212:213], off
	s_waitcnt vmcnt(8)
	s_waitcnt lgkmcnt(0)
	s_barrier
	s_setprio 1
	v_mfma_i32_16x16x64_i8 v[76:79], v[20:23], v[170:173], v[76:79]
	v_mfma_i32_16x16x64_i8 v[72:75], v[56:59], v[170:173], v[72:75]
	v_mfma_i32_16x16x64_i8 v[52:55], v[20:23], v[178:181], v[52:55]
	v_mfma_i32_16x16x64_i8 v[44:47], v[56:59], v[178:181], v[44:47]
	v_mfma_i32_16x16x64_i8 v[36:39], v[20:23], v[186:189], v[36:39]
	v_mfma_i32_16x16x64_i8 v[24:27], v[56:59], v[186:189], v[24:27]
	v_mfma_i32_16x16x64_i8 v[12:15], v[20:23], v[200:203], v[12:15]
	v_mfma_i32_16x16x64_i8 v[4:7], v[56:59], v[200:203], v[4:7]
	v_mfma_i32_16x16x64_i8 v[76:79], v[32:35], v[174:177], v[76:79]
	v_mfma_i32_16x16x64_i8 v[72:75], v[60:63], v[174:177], v[72:75]
	v_mfma_i32_16x16x64_i8 v[52:55], v[32:35], v[182:185], v[52:55]
	v_mfma_i32_16x16x64_i8 v[44:47], v[60:63], v[182:185], v[44:47]
	v_mfma_i32_16x16x64_i8 v[36:39], v[32:35], v[194:197], v[36:39]
	v_mfma_i32_16x16x64_i8 v[24:27], v[60:63], v[194:197], v[24:27]
	v_mfma_i32_16x16x64_i8 v[12:15], v[32:35], v[204:207], v[12:15]
	v_mfma_i32_16x16x64_i8 v[4:7], v[60:63], v[204:207], v[4:7]
	v_mfma_i32_16x16x64_i8 v[48:51], v[154:157], v[178:181], v[48:51]
	v_mfma_i32_16x16x64_i8 v[40:43], v[162:165], v[178:181], v[40:43]
	v_mfma_i32_16x16x64_i8 v[28:31], v[154:157], v[186:189], v[28:31]
	v_mfma_i32_16x16x64_i8 v[16:19], v[162:165], v[186:189], v[16:19]
	v_mfma_i32_16x16x64_i8 v[8:11], v[154:157], v[200:203], v[8:11]
	v_mfma_i32_16x16x64_i8 v[0:3], v[162:165], v[200:203], v[0:3]
	v_mfma_i32_16x16x64_i8 v[20:23], v[154:157], v[170:173], v[68:71]
	v_mfma_i32_16x16x64_i8 v[32:35], v[162:165], v[170:173], v[64:67]
	v_mfma_i32_16x16x64_i8 v[48:51], v[158:161], v[182:185], v[48:51]
	v_mfma_i32_16x16x64_i8 v[40:43], v[166:169], v[182:185], v[40:43]
	v_mfma_i32_16x16x64_i8 v[28:31], v[158:161], v[194:197], v[28:31]
	v_mfma_i32_16x16x64_i8 v[16:19], v[166:169], v[194:197], v[16:19]
	v_mfma_i32_16x16x64_i8 v[8:11], v[158:161], v[204:207], v[8:11]
	v_mfma_i32_16x16x64_i8 v[0:3], v[166:169], v[204:207], v[0:3]
	v_mfma_i32_16x16x64_i8 v[20:23], v[158:161], v[174:177], v[20:23]
	v_mfma_i32_16x16x64_i8 v[32:35], v[166:169], v[174:177], v[32:35]
	s_setprio 0
	s_barrier
	s_add_i32 s12, 0, 0x18000
	s_add_i32 s13, 0, 0x1c000
	v_add_u32_e32 v68, s12, v198
	v_add_u32_e32 v166, s13, v198
	ds_read_b128 v[56:59], v68
	ds_read_b128 v[60:63], v68 offset:1024
	ds_read_b128 v[64:67], v68 offset:2048
	ds_read_b128 v[68:71], v68 offset:3072
	ds_read_b128 v[154:157], v166
	ds_read_b128 v[158:161], v166 offset:1024
	ds_read_b128 v[162:165], v166 offset:2048
	ds_read_b128 v[166:169], v166 offset:3072
	s_add_u32 s44, s52, 0x80000
	s_addc_u32 s45, s53, 0
	s_mov_b32 m0, s62
	v_lshl_add_u64 v[214:215], s[44:45], 0, v[148:149]
	ds_read_b128 v[170:173], v199 offset:32768
	ds_read_b128 v[174:177], v199 offset:33792
	ds_read_b128 v[178:181], v199 offset:34816
	ds_read_b128 v[182:185], v199 offset:35840
	ds_read_b128 v[186:189], v199 offset:36864
	ds_read_b128 v[194:197], v199 offset:37888
	ds_read_b128 v[200:203], v199 offset:38912
	ds_read_b128 v[204:207], v199 offset:39936
	global_load_lds_dwordx4 v[214:215], off
	v_lshl_add_u64 v[214:215], s[44:45], 0, v[146:147]
	s_mov_b32 m0, s63
	s_nop 0
	global_load_lds_dwordx4 v[214:215], off
	s_waitcnt vmcnt(8)
	s_waitcnt lgkmcnt(0)
	s_barrier
	s_setprio 1
	v_mfma_i32_16x16x64_i8 v[140:143], v[56:59], v[170:173], v[140:143]
	v_mfma_i32_16x16x64_i8 v[136:139], v[64:67], v[170:173], v[136:139]
	v_mfma_i32_16x16x64_i8 v[132:135], v[56:59], v[178:181], v[132:135]
	v_mfma_i32_16x16x64_i8 v[124:127], v[64:67], v[178:181], v[124:127]
	v_mfma_i32_16x16x64_i8 v[116:119], v[56:59], v[186:189], v[116:119]
	v_mfma_i32_16x16x64_i8 v[108:111], v[64:67], v[186:189], v[108:111]
	v_mfma_i32_16x16x64_i8 v[100:103], v[56:59], v[200:203], v[100:103]
	v_mfma_i32_16x16x64_i8 v[92:95], v[64:67], v[200:203], v[92:95]
	v_mfma_i32_16x16x64_i8 v[140:143], v[60:63], v[174:177], v[140:143]
	v_mfma_i32_16x16x64_i8 v[136:139], v[68:71], v[174:177], v[136:139]
	v_mfma_i32_16x16x64_i8 v[132:135], v[60:63], v[182:185], v[132:135]
	v_mfma_i32_16x16x64_i8 v[124:127], v[68:71], v[182:185], v[124:127]
	v_mfma_i32_16x16x64_i8 v[116:119], v[60:63], v[194:197], v[116:119]
	v_mfma_i32_16x16x64_i8 v[108:111], v[68:71], v[194:197], v[108:111]
	v_mfma_i32_16x16x64_i8 v[100:103], v[60:63], v[204:207], v[100:103]
	v_mfma_i32_16x16x64_i8 v[92:95], v[68:71], v[204:207], v[92:95]
	v_mfma_i32_16x16x64_i8 v[128:131], v[154:157], v[170:173], v[128:131]
	v_mfma_i32_16x16x64_i8 v[120:123], v[162:165], v[170:173], v[120:123]
	v_mfma_i32_16x16x64_i8 v[112:115], v[154:157], v[178:181], v[112:115]
	v_mfma_i32_16x16x64_i8 v[104:107], v[162:165], v[178:181], v[104:107]
	v_mfma_i32_16x16x64_i8 v[96:99], v[154:157], v[186:189], v[96:99]
	v_mfma_i32_16x16x64_i8 v[88:91], v[162:165], v[186:189], v[88:91]
	v_mfma_i32_16x16x64_i8 v[84:87], v[154:157], v[200:203], v[84:87]
	v_mfma_i32_16x16x64_i8 v[80:83], v[162:165], v[200:203], v[80:83]
	v_mfma_i32_16x16x64_i8 v[128:131], v[158:161], v[174:177], v[128:131]
	v_mfma_i32_16x16x64_i8 v[120:123], v[166:169], v[174:177], v[120:123]
	v_mfma_i32_16x16x64_i8 v[112:115], v[158:161], v[182:185], v[112:115]
	v_mfma_i32_16x16x64_i8 v[104:107], v[166:169], v[182:185], v[104:107]
	v_mfma_i32_16x16x64_i8 v[96:99], v[158:161], v[194:197], v[96:99]
	v_mfma_i32_16x16x64_i8 v[88:91], v[166:169], v[194:197], v[88:91]
	v_mfma_i32_16x16x64_i8 v[84:87], v[158:161], v[204:207], v[84:87]
	v_mfma_i32_16x16x64_i8 v[80:83], v[166:169], v[204:207], v[80:83]
	s_setprio 0
	s_barrier
	s_add_i32 s12, s12, s0
	v_lshl_add_u64 v[190:191], v[190:191], 0, s[34:35]
	s_mov_b32 m0, s12
	ds_read_b128 v[170:173], v199 offset:49152
	ds_read_b128 v[174:177], v199 offset:50176
	ds_read_b128 v[178:181], v199 offset:51200
	ds_read_b128 v[182:185], v199 offset:52224
	ds_read_b128 v[186:189], v199 offset:53248
	ds_read_b128 v[194:197], v199 offset:54272
	ds_read_b128 v[200:203], v199 offset:55296
	ds_read_b128 v[204:207], v199 offset:56320
	global_load_lds_dwordx4 v[190:191], off
	s_add_i32 m0, s12, 0x2000
	s_add_u32 s24, s24, 0x80080
	v_lshl_add_u64 v[190:191], v[208:209], 0, s[34:35]
	s_addc_u32 s25, s25, 0
	s_add_i32 s12, s13, s0
	global_load_lds_dwordx4 v[190:191], off
	v_lshl_add_u64 v[190:191], s[24:25], 0, v[192:193]
	s_mov_b32 m0, s12
	s_nop 0
	global_load_lds_dwordx4 v[190:191], off
	v_lshl_add_u64 v[190:191], s[24:25], 0, v[144:145]
	s_add_i32 m0, s12, 0x2000
	s_nop 0
	global_load_lds_dwordx4 v[190:191], off
	v_lshl_add_u64 v[190:191], v[210:211], 0, s[34:35]
	s_mov_b32 m0, s74
	s_nop 0
	global_load_lds_dwordx4 v[190:191], off
	v_lshl_add_u64 v[190:191], v[212:213], 0, s[34:35]
	s_mov_b32 m0, s75
	s_nop 0
	global_load_lds_dwordx4 v[190:191], off
	s_waitcnt vmcnt(8)
	s_waitcnt lgkmcnt(0)
	s_barrier
	s_setprio 1
	v_mfma_i32_16x16x64_i8 v[76:79], v[56:59], v[170:173], v[76:79]
	v_mfma_i32_16x16x64_i8 v[72:75], v[64:67], v[170:173], v[72:75]
	v_mfma_i32_16x16x64_i8 v[52:55], v[56:59], v[178:181], v[52:55]
	v_mfma_i32_16x16x64_i8 v[44:47], v[64:67], v[178:181], v[44:47]
	v_mfma_i32_16x16x64_i8 v[36:39], v[56:59], v[186:189], v[36:39]
	v_mfma_i32_16x16x64_i8 v[24:27], v[64:67], v[186:189], v[24:27]
	v_mfma_i32_16x16x64_i8 v[12:15], v[56:59], v[200:203], v[12:15]
	v_mfma_i32_16x16x64_i8 v[4:7], v[64:67], v[200:203], v[4:7]
	v_mfma_i32_16x16x64_i8 v[76:79], v[60:63], v[174:177], v[76:79]
	v_mfma_i32_16x16x64_i8 v[72:75], v[68:71], v[174:177], v[72:75]
	v_mfma_i32_16x16x64_i8 v[52:55], v[60:63], v[182:185], v[52:55]
	v_mfma_i32_16x16x64_i8 v[44:47], v[68:71], v[182:185], v[44:47]
	v_mfma_i32_16x16x64_i8 v[36:39], v[60:63], v[194:197], v[36:39]
	v_mfma_i32_16x16x64_i8 v[24:27], v[68:71], v[194:197], v[24:27]
	v_mfma_i32_16x16x64_i8 v[12:15], v[60:63], v[204:207], v[12:15]
	v_mfma_i32_16x16x64_i8 v[4:7], v[68:71], v[204:207], v[4:7]
	v_mfma_i32_16x16x64_i8 v[20:23], v[154:157], v[170:173], v[20:23]
	v_mfma_i32_16x16x64_i8 v[68:71], v[158:161], v[174:177], v[20:23]
	v_mfma_i32_16x16x64_i8 v[20:23], v[162:165], v[170:173], v[32:35]
	v_mfma_i32_16x16x64_i8 v[64:67], v[166:169], v[174:177], v[20:23]
	v_mfma_i32_16x16x64_i8 v[20:23], v[154:157], v[178:181], v[48:51]
	v_mfma_i32_16x16x64_i8 v[48:51], v[158:161], v[182:185], v[20:23]
	v_mfma_i32_16x16x64_i8 v[20:23], v[162:165], v[178:181], v[40:43]
	v_mfma_i32_16x16x64_i8 v[40:43], v[166:169], v[182:185], v[20:23]
	v_mfma_i32_16x16x64_i8 v[20:23], v[154:157], v[186:189], v[28:31]
	v_mfma_i32_16x16x64_i8 v[16:19], v[162:165], v[186:189], v[16:19]
	v_mfma_i32_16x16x64_i8 v[8:11], v[154:157], v[200:203], v[8:11]
	v_mfma_i32_16x16x64_i8 v[0:3], v[162:165], v[200:203], v[0:3]
	v_mfma_i32_16x16x64_i8 v[28:31], v[158:161], v[194:197], v[20:23]
	v_mfma_i32_16x16x64_i8 v[16:19], v[166:169], v[194:197], v[16:19]
	v_mfma_i32_16x16x64_i8 v[8:11], v[158:161], v[204:207], v[8:11]
	v_mfma_i32_16x16x64_i8 v[0:3], v[166:169], v[204:207], v[0:3]
	s_setprio 0
	s_barrier
	s_add_i32 s29, s29, 2
	s_add_u32 s50, s50, 0x100
	s_addc_u32 s51, s51, 0
	s_add_u32 s10, s10, 0x100
	s_addc_u32 s11, s11, 0
	s_cmp_lt_u32 s29, 30
	s_cbranch_scc1 .LBB0_552
	s_andn2_b64 vcc, exec, s[38:39]
	s_cbranch_vccnz .LBB0_555
	s_barrier

; __device__ __forceinline__ void glds_saddr(unsigned voff, const void* sbase, unsigned lds_dst) { unsigned keep;
;     asm volatile("s_mov_b32 %0, m0\n\ts_mov_b32 m0, %3\n\ts_nop 0\n\tglobal_load_lds_dwordx4 %1, %2\n\ts_mov_b32 m0, %0" : "=&s"(keep) : "v"(voff), "s"(sbase), "s"(lds_dst) : "memory"); }
.LBB0_615:
	v_add_u32_e32 v128, 0x10000, v132
	v_add_u32_e32 v129, 0x14000, v132
	ds_read_b128 v[134:137], v128
	ds_read_b128 v[138:141], v128 offset:1024
	ds_read_b128 v[142:145], v128 offset:2048
	ds_read_b128 v[146:149], v128 offset:3072
	ds_read_b128 v[150:153], v129
	ds_read_b128 v[154:157], v129 offset:1024
	ds_read_b128 v[158:161], v129 offset:2048
	ds_read_b128 v[162:165], v129 offset:3072
	s_add_u32 s94, s60, 0x180
	s_addc_u32 s95, s61, 0
	s_add_u32 s62, s56, 0x100
	s_addc_u32 s63, s57, 0
	s_add_u32 s90, s60, 0x100
	s_addc_u32 s91, s61, 0
	ds_read_b128 v[166:169], v133
	ds_read_b128 v[170:173], v133 offset:1024
	ds_read_b128 v[174:177], v133 offset:2048
	ds_read_b128 v[178:181], v133 offset:3072
	ds_read_b128 v[182:185], v133 offset:4096
	ds_read_b128 v[186:189], v133 offset:5120
	ds_read_b128 v[194:197], v133 offset:6144
	ds_read_b128 v[198:201], v133 offset:7168
	s_add_u32 s12, s60, 0x188080
	s_addc_u32 s13, s61, 0
	s_mov_b32 s25, m0
	s_mov_b32 m0, s79
	s_nop 0
	global_load_lds_dwordx4 v130, s[12:13]
	s_mov_b32 m0, s25
	s_nop 0
	s_mov_b32 s25, m0
	s_mov_b32 m0, s96
	s_nop 0
	global_load_lds_dwordx4 v131, s[12:13]
	s_mov_b32 m0, s25
	s_waitcnt vmcnt(8)
	s_waitcnt lgkmcnt(0)
	s_barrier
	s_setprio 1
	v_mfma_f32_16x16x32_bf16 v[124:127], v[134:137], v[166:169], v[124:127]
	v_mfma_f32_16x16x32_bf16 v[120:123], v[142:145], v[166:169], v[120:123]
	v_mfma_f32_16x16x32_bf16 v[112:115], v[134:137], v[174:177], v[112:115]
	v_mfma_f32_16x16x32_bf16 v[104:107], v[142:145], v[174:177], v[104:107]
	v_mfma_f32_16x16x32_bf16 v[96:99], v[134:137], v[182:185], v[96:99]
	v_mfma_f32_16x16x32_bf16 v[88:91], v[142:145], v[182:185], v[88:91]
	v_mfma_f32_16x16x32_bf16 v[80:83], v[134:137], v[194:197], v[80:83]
	v_mfma_f32_16x16x32_bf16 v[72:75], v[142:145], v[194:197], v[72:75]
	v_mfma_f32_16x16x32_bf16 v[124:127], v[138:141], v[170:173], v[124:127]
	v_mfma_f32_16x16x32_bf16 v[120:123], v[146:149], v[170:173], v[120:123]
	v_mfma_f32_16x16x32_bf16 v[112:115], v[138:141], v[178:181], v[112:115]
	v_mfma_f32_16x16x32_bf16 v[104:107], v[146:149], v[178:181], v[104:107]
	v_mfma_f32_16x16x32_bf16 v[96:99], v[138:141], v[186:189], v[96:99]
	v_mfma_f32_16x16x32_bf16 v[88:91], v[146:149], v[186:189], v[88:91]
	v_mfma_f32_16x16x32_bf16 v[80:83], v[138:141], v[198:201], v[80:83]
	v_mfma_f32_16x16x32_bf16 v[72:75], v[146:149], v[198:201], v[72:75]
	v_mfma_f32_16x16x32_bf16 v[116:119], v[150:153], v[166:169], v[116:119]
	v_mfma_f32_16x16x32_bf16 v[108:111], v[158:161], v[166:169], v[108:111]
	v_mfma_f32_16x16x32_bf16 v[100:103], v[150:153], v[174:177], v[100:103]
	v_mfma_f32_16x16x32_bf16 v[92:95], v[158:161], v[174:177], v[92:95]
	v_mfma_f32_16x16x32_bf16 v[84:87], v[150:153], v[182:185], v[84:87]
	v_mfma_f32_16x16x32_bf16 v[76:79], v[158:161], v[182:185], v[76:79]
	v_mfma_f32_16x16x32_bf16 v[68:71], v[150:153], v[194:197], v[68:71]
	v_mfma_f32_16x16x32_bf16 v[64:67], v[158:161], v[194:197], v[64:67]
	v_mfma_f32_16x16x32_bf16 v[116:119], v[154:157], v[170:173], v[116:119]
	v_mfma_f32_16x16x32_bf16 v[108:111], v[162:165], v[170:173], v[108:111]
	v_mfma_f32_16x16x32_bf16 v[100:103], v[154:157], v[178:181], v[100:103]
	v_mfma_f32_16x16x32_bf16 v[92:95], v[162:165], v[178:181], v[92:95]
	v_mfma_f32_16x16x32_bf16 v[84:87], v[154:157], v[186:189], v[84:87]
	v_mfma_f32_16x16x32_bf16 v[76:79], v[162:165], v[186:189], v[76:79]
	v_mfma_f32_16x16x32_bf16 v[68:71], v[154:157], v[198:201], v[68:71]
	v_mfma_f32_16x16x32_bf16 v[64:67], v[162:165], v[198:201], v[64:67]
	s_setprio 0
	s_barrier
	ds_read_b128 v[166:169], v133 offset:16384
	ds_read_b128 v[170:173], v133 offset:17408
	ds_read_b128 v[174:177], v133 offset:18432
	ds_read_b128 v[178:181], v133 offset:19456
	ds_read_b128 v[182:185], v133 offset:20480
	ds_read_b128 v[186:189], v133 offset:21504
	ds_read_b128 v[194:197], v133 offset:22528
	ds_read_b128 v[198:201], v133 offset:23552
	s_mov_b32 s12, m0
	s_mov_b32 m0, s4
	s_nop 0
	global_load_lds_dwordx4 v130, s[62:63]
	s_mov_b32 m0, s12
	s_nop 0
	s_mov_b32 s12, m0
	s_mov_b32 m0, s5
	s_nop 0
	global_load_lds_dwordx4 v131, s[62:63]
	s_mov_b32 m0, s12
	s_add_u32 s12, s56, 0x188100
	s_addc_u32 s13, s57, 0
	s_mov_b32 s25, m0
	s_mov_b32 m0, s6
	s_nop 0
	global_load_lds_dwordx4 v130, s[12:13]
	s_mov_b32 m0, s25
	s_nop 0
	s_mov_b32 s25, m0
	s_mov_b32 m0, s7
	s_nop 0
	global_load_lds_dwordx4 v131, s[12:13]
	s_mov_b32 m0, s25
	s_mov_b32 s12, m0
	s_mov_b32 m0, s0
	s_nop 0
	global_load_lds_dwordx4 v130, s[90:91]
	s_mov_b32 m0, s12
	s_nop 0
	s_mov_b32 s12, m0
	s_mov_b32 m0, s44
	s_nop 0
	global_load_lds_dwordx4 v131, s[90:91]
	s_mov_b32 m0, s12
	s_waitcnt vmcnt(8)
	s_waitcnt lgkmcnt(0)
	s_barrier
	s_setprio 1
	v_mfma_f32_16x16x32_bf16 v[60:63], v[134:137], v[166:169], v[60:63]
	v_mfma_f32_16x16x32_bf16 v[56:59], v[142:145], v[166:169], v[56:59]
	v_mfma_f32_16x16x32_bf16 v[52:55], v[134:137], v[174:177], v[52:55]
	v_mfma_f32_16x16x32_bf16 v[40:43], v[142:145], v[174:177], v[40:43]
	v_mfma_f32_16x16x32_bf16 v[36:39], v[134:137], v[182:185], v[36:39]
	v_mfma_f32_16x16x32_bf16 v[24:27], v[142:145], v[182:185], v[24:27]
	v_mfma_f32_16x16x32_bf16 v[20:23], v[134:137], v[194:197], v[20:23]
	v_mfma_f32_16x16x32_bf16 v[8:11], v[142:145], v[194:197], v[8:11]
	v_mfma_f32_16x16x32_bf16 v[60:63], v[138:141], v[170:173], v[60:63]
	v_mfma_f32_16x16x32_bf16 v[56:59], v[146:149], v[170:173], v[56:59]
	v_mfma_f32_16x16x32_bf16 v[52:55], v[138:141], v[178:181], v[52:55]
	v_mfma_f32_16x16x32_bf16 v[40:43], v[146:149], v[178:181], v[40:43]
	v_mfma_f32_16x16x32_bf16 v[36:39], v[138:141], v[186:189], v[36:39]
	v_mfma_f32_16x16x32_bf16 v[24:27], v[146:149], v[186:189], v[24:27]
	v_mfma_f32_16x16x32_bf16 v[20:23], v[138:141], v[198:201], v[20:23]
	v_mfma_f32_16x16x32_bf16 v[8:11], v[146:149], v[198:201], v[8:11]
	v_mfma_f32_16x16x32_bf16 v[48:51], v[150:153], v[166:169], v[48:51]
	v_mfma_f32_16x16x32_bf16 v[44:47], v[158:161], v[166:169], v[44:47]
	v_mfma_f32_16x16x32_bf16 v[32:35], v[150:153], v[174:177], v[32:35]
	v_mfma_f32_16x16x32_bf16 v[28:31], v[158:161], v[174:177], v[28:31]
	v_mfma_f32_16x16x32_bf16 v[16:19], v[150:153], v[182:185], v[16:19]
	v_mfma_f32_16x16x32_bf16 v[12:15], v[158:161], v[182:185], v[12:15]
	v_mfma_f32_16x16x32_bf16 v[4:7], v[150:153], v[194:197], v[4:7]
	v_mfma_f32_16x16x32_bf16 v[0:3], v[158:161], v[194:197], v[0:3]
	v_mfma_f32_16x16x32_bf16 v[48:51], v[154:157], v[170:173], v[48:51]
	v_mfma_f32_16x16x32_bf16 v[44:47], v[162:165], v[170:173], v[44:47]
	v_mfma_f32_16x16x32_bf16 v[32:35], v[154:157], v[178:181], v[32:35]
	v_mfma_f32_16x16x32_bf16 v[28:31], v[162:165], v[178:181], v[28:31]
	v_mfma_f32_16x16x32_bf16 v[16:19], v[154:157], v[186:189], v[16:19]
	v_mfma_f32_16x16x32_bf16 v[12:15], v[162:165], v[186:189], v[12:15]
	v_mfma_f32_16x16x32_bf16 v[4:7], v[154:157], v[198:201], v[4:7]
	v_mfma_f32_16x16x32_bf16 v[0:3], v[162:165], v[198:201], v[0:3]
	s_setprio 0
	s_barrier
	v_add_u32_e32 v134, 0x18000, v132
	v_add_u32_e32 v135, 0x1c000, v132
	ds_read_b128 v[136:139], v134
	ds_read_b128 v[140:143], v134 offset:1024
	ds_read_b128 v[144:147], v134 offset:2048
	ds_read_b128 v[148:151], v134 offset:3072
	ds_read_b128 v[152:155], v135
	ds_read_b128 v[156:159], v135 offset:1024
	ds_read_b128 v[160:163], v135 offset:2048
	ds_read_b128 v[164:167], v135 offset:3072
	ds_read_b128 v[168:171], v133 offset:32768
	ds_read_b128 v[172:175], v133 offset:33792
	ds_read_b128 v[176:179], v133 offset:34816
	ds_read_b128 v[180:183], v133 offset:35840
	ds_read_b128 v[184:187], v133 offset:36864
	ds_read_b128 v[188:191], v133 offset:37888
	ds_read_b128 v[194:197], v133 offset:38912
	ds_read_b128 v[198:201], v133 offset:39936
	s_add_u32 s12, s60, 0x188100
	s_addc_u32 s13, s61, 0
	s_mov_b32 s25, m0
	s_mov_b32 m0, s45
	s_nop 0
	global_load_lds_dwordx4 v130, s[12:13]
	s_mov_b32 m0, s25
	s_nop 0
	s_mov_b32 s25, m0
	s_mov_b32 m0, s58
	s_nop 0
	global_load_lds_dwordx4 v131, s[12:13]
	s_mov_b32 m0, s25
	s_waitcnt vmcnt(8)
	s_waitcnt lgkmcnt(0)
	s_barrier
	s_setprio 1
	v_mfma_f32_16x16x32_bf16 v[124:127], v[136:139], v[168:171], v[124:127]
	v_mfma_f32_16x16x32_bf16 v[120:123], v[144:147], v[168:171], v[120:123]
	v_mfma_f32_16x16x32_bf16 v[112:115], v[136:139], v[176:179], v[112:115]
	v_mfma_f32_16x16x32_bf16 v[104:107], v[144:147], v[176:179], v[104:107]
	v_mfma_f32_16x16x32_bf16 v[96:99], v[136:139], v[184:187], v[96:99]
	v_mfma_f32_16x16x32_bf16 v[88:91], v[144:147], v[184:187], v[88:91]
	v_mfma_f32_16x16x32_bf16 v[80:83], v[136:139], v[194:197], v[80:83]
	v_mfma_f32_16x16x32_bf16 v[72:75], v[144:147], v[194:197], v[72:75]
	v_mfma_f32_16x16x32_bf16 v[124:127], v[140:143], v[172:175], v[124:127]
	v_mfma_f32_16x16x32_bf16 v[120:123], v[148:151], v[172:175], v[120:123]
	v_mfma_f32_16x16x32_bf16 v[112:115], v[140:143], v[180:183], v[112:115]
	v_mfma_f32_16x16x32_bf16 v[104:107], v[148:151], v[180:183], v[104:107]
	v_mfma_f32_16x16x32_bf16 v[96:99], v[140:143], v[188:191], v[96:99]
	v_mfma_f32_16x16x32_bf16 v[88:91], v[148:151], v[188:191], v[88:91]
	v_mfma_f32_16x16x32_bf16 v[80:83], v[140:143], v[198:201], v[80:83]
	v_mfma_f32_16x16x32_bf16 v[72:75], v[148:151], v[198:201], v[72:75]
	v_mfma_f32_16x16x32_bf16 v[116:119], v[152:155], v[168:171], v[116:119]
	v_mfma_f32_16x16x32_bf16 v[108:111], v[160:163], v[168:171], v[108:111]
	v_mfma_f32_16x16x32_bf16 v[100:103], v[152:155], v[176:179], v[100:103]
	v_mfma_f32_16x16x32_bf16 v[92:95], v[160:163], v[176:179], v[92:95]
	v_mfma_f32_16x16x32_bf16 v[84:87], v[152:155], v[184:187], v[84:87]
	v_mfma_f32_16x16x32_bf16 v[76:79], v[160:163], v[184:187], v[76:79]
	v_mfma_f32_16x16x32_bf16 v[68:71], v[152:155], v[194:197], v[68:71]
	v_mfma_f32_16x16x32_bf16 v[64:67], v[160:163], v[194:197], v[64:67]
	v_mfma_f32_16x16x32_bf16 v[116:119], v[156:159], v[172:175], v[116:119]
	v_mfma_f32_16x16x32_bf16 v[108:111], v[164:167], v[172:175], v[108:111]
	v_mfma_f32_16x16x32_bf16 v[100:103], v[156:159], v[180:183], v[100:103]
	v_mfma_f32_16x16x32_bf16 v[92:95], v[164:167], v[180:183], v[92:95]
	v_mfma_f32_16x16x32_bf16 v[84:87], v[156:159], v[188:191], v[84:87]
	v_mfma_f32_16x16x32_bf16 v[76:79], v[164:167], v[188:191], v[76:79]
	v_mfma_f32_16x16x32_bf16 v[68:71], v[156:159], v[198:201], v[68:71]
	v_mfma_f32_16x16x32_bf16 v[64:67], v[164:167], v[198:201], v[64:67]
	s_setprio 0
	s_barrier
; #define PG8_MMA(ai, bj, At, Bt) do { __builtin_amdgcn_s_setprio(1); _Pragma("unroll") for (int m = 0; m < 4; ++m) _Pragma("unroll") for (int n = 0; n < 2; ++n) _Pragma("unroll") for (int k = 0; k < 2; ++k) \
;         acc[ai][bj][m][n] = __builtin_amdgcn_mfma_f32_16x16x32_bf16(Bt[n][k], At[m][k], acc[ai][bj][m][n], 0, 0, 0); __builtin_amdgcn_s_setprio(0); } while (0)
; #define PG8_MMA8(ai, bj, At, Bt) do { __builtin_amdgcn_s_setprio(1); _Pragma("unroll") for (int m = 0; m < 4; ++m) _Pragma("unroll") for (int n = 0; n < 2; ++n) \
;         acc[ai][bj][m][n] = __builtin_amdgcn_mfma_scale_f32_16x16x128_f8f6f4(cat8(Bt[n][0], Bt[n][1]), cat8(At[m][0], At[m][1]), acc[ai][bj][m][n], 0, 0, 0, F8_SC_W, 0, F8_SC_H); __builtin_amdgcn_s_setprio(0); } while (0)
; #define PG8_ITER_HEAD() \
;             const bool last = (t == nt - 2); \
;             const char* a1 = cA + (size_t)(t + 1) * kstep; \
;             const char* a2 = last ? nA : cA + (size_t)(t + 2) * kstep; const char* b2 = last ? nB : cB + (size_t)(t + 2) * kstep; \
;             const char* a3 = a2 + kstep; const char* b3 = b2 + kstep; \
;             if (last && has_next) S.a_ready(nxt);
;     ...
;         } else if constexpr (SP2 && KS8 > 0) {
;             for (; t < KS8; t += 2) { PG8_ITER_HEAD() PG8_ITER_SP2(PG8_MMA) }
;             for (; t < nt; t += 2) { PG8_ITER_HEAD() PG8_ITER_SP2(PG8_MMA8) }
	ds_read_b128 v[168:171], v133 offset:49152
	ds_read_b128 v[172:175], v133 offset:50176
	ds_read_b128 v[176:179], v133 offset:51200
	ds_read_b128 v[180:183], v133 offset:52224
	ds_read_b128 v[184:187], v133 offset:53248
	ds_read_b128 v[188:191], v133 offset:54272
	ds_read_b128 v[194:197], v133 offset:55296
	ds_read_b128 v[198:201], v133 offset:56320
	s_add_u32 s12, s56, 0x180
	s_addc_u32 s13, s57, 0
	s_mov_b32 s25, m0
	s_mov_b32 m0, s73
	s_nop 0
	global_load_lds_dwordx4 v130, s[12:13]
	s_mov_b32 m0, s25
	s_nop 0
	s_mov_b32 s25, m0
	s_mov_b32 m0, s74
	s_nop 0
	global_load_lds_dwordx4 v131, s[12:13]
	s_mov_b32 m0, s25
	s_add_u32 s12, s56, 0x188180
	s_addc_u32 s13, s57, 0
	s_mov_b32 s25, m0
	s_mov_b32 m0, s77
	s_nop 0
	global_load_lds_dwordx4 v130, s[12:13]
	s_mov_b32 m0, s25
	s_nop 0
	s_mov_b32 s25, m0
	s_mov_b32 m0, s78
	s_nop 0
	global_load_lds_dwordx4 v131, s[12:13]
	s_mov_b32 m0, s25
	s_mov_b32 s12, m0
	s_mov_b32 m0, s75
	s_nop 0
	global_load_lds_dwordx4 v130, s[94:95]
	s_mov_b32 m0, s12
	s_nop 0
	s_mov_b32 s12, m0
	s_mov_b32 m0, s76
	s_nop 0
	global_load_lds_dwordx4 v131, s[94:95]
	s_mov_b32 m0, s12
	s_waitcnt vmcnt(8)
	s_waitcnt lgkmcnt(0)
	s_barrier
	s_setprio 1
	v_mfma_f32_16x16x32_bf16 v[60:63], v[136:139], v[168:171], v[60:63]
	v_mfma_f32_16x16x32_bf16 v[56:59], v[144:147], v[168:171], v[56:59]
	v_mfma_f32_16x16x32_bf16 v[52:55], v[136:139], v[176:179], v[52:55]
	v_mfma_f32_16x16x32_bf16 v[40:43], v[144:147], v[176:179], v[40:43]
	v_mfma_f32_16x16x32_bf16 v[36:39], v[136:139], v[184:187], v[36:39]
	v_mfma_f32_16x16x32_bf16 v[24:27], v[144:147], v[184:187], v[24:27]
	v_mfma_f32_16x16x32_bf16 v[20:23], v[136:139], v[194:197], v[20:23]
	v_mfma_f32_16x16x32_bf16 v[8:11], v[144:147], v[194:197], v[8:11]
	v_mfma_f32_16x16x32_bf16 v[60:63], v[140:143], v[172:175], v[60:63]
	v_mfma_f32_16x16x32_bf16 v[56:59], v[148:151], v[172:175], v[56:59]
	v_mfma_f32_16x16x32_bf16 v[52:55], v[140:143], v[180:183], v[52:55]
	v_mfma_f32_16x16x32_bf16 v[40:43], v[148:151], v[180:183], v[40:43]
	v_mfma_f32_16x16x32_bf16 v[36:39], v[140:143], v[188:191], v[36:39]
	v_mfma_f32_16x16x32_bf16 v[24:27], v[148:151], v[188:191], v[24:27]
	v_mfma_f32_16x16x32_bf16 v[20:23], v[140:143], v[198:201], v[20:23]
	v_mfma_f32_16x16x32_bf16 v[8:11], v[148:151], v[198:201], v[8:11]
	v_mfma_f32_16x16x32_bf16 v[48:51], v[152:155], v[168:171], v[48:51]
	v_mfma_f32_16x16x32_bf16 v[44:47], v[160:163], v[168:171], v[44:47]
	v_mfma_f32_16x16x32_bf16 v[32:35], v[152:155], v[176:179], v[32:35]
	v_mfma_f32_16x16x32_bf16 v[28:31], v[160:163], v[176:179], v[28:31]
	v_mfma_f32_16x16x32_bf16 v[16:19], v[152:155], v[184:187], v[16:19]
	v_mfma_f32_16x16x32_bf16 v[12:15], v[160:163], v[184:187], v[12:15]
	v_mfma_f32_16x16x32_bf16 v[4:7], v[152:155], v[194:197], v[4:7]
	v_mfma_f32_16x16x32_bf16 v[0:3], v[160:163], v[194:197], v[0:3]
	v_mfma_f32_16x16x32_bf16 v[48:51], v[156:159], v[172:175], v[48:51]
	v_mfma_f32_16x16x32_bf16 v[44:47], v[164:167], v[172:175], v[44:47]
	v_mfma_f32_16x16x32_bf16 v[32:35], v[156:159], v[180:183], v[32:35]
	v_mfma_f32_16x16x32_bf16 v[28:31], v[164:167], v[180:183], v[28:31]
	v_mfma_f32_16x16x32_bf16 v[16:19], v[156:159], v[188:191], v[16:19]
	v_mfma_f32_16x16x32_bf16 v[12:15], v[164:167], v[188:191], v[12:15]
	v_mfma_f32_16x16x32_bf16 v[4:7], v[156:159], v[198:201], v[4:7]
	v_mfma_f32_16x16x32_bf16 v[0:3], v[164:167], v[198:201], v[0:3]
	s_setprio 0
	s_barrier
	s_add_i32 s24, s24, 2
	s_cmp_lt_u32 s24, 22
	s_mov_b64 s[56:57], s[62:63]
	s_mov_b64 s[60:61], s[90:91]
	s_cbranch_scc1 .LBB0_615
	s_add_u32 s60, s52, 0xc00
	s_addc_u32 s61, s53, 0
	s_add_u32 s62, s50, 0xd00
	s_addc_u32 s63, s51, 0
	s_mov_b32 s90, 22
.LBB0_617:
	ds_read_b128 v[136:139], v128
	ds_read_b128 v[140:143], v128 offset:1024
	ds_read_b128 v[144:147], v128 offset:2048
	ds_read_b128 v[148:151], v128 offset:3072
	ds_read_b128 v[152:155], v129
	ds_read_b128 v[156:159], v129 offset:1024
	ds_read_b128 v[160:163], v129 offset:2048
	ds_read_b128 v[164:167], v129 offset:3072
	s_add_u32 s50, s60, 0x100
	s_addc_u32 s51, s61, 0
	s_cmpk_eq_i32 s90, 0x5e
	s_cselect_b32 s24, s40, s50
	s_cselect_b32 s25, s41, s51
	s_cselect_b32 s56, s46, s62
	s_cselect_b32 s57, s47, s63
	s_add_u32 s52, s24, 0x80
	s_addc_u32 s53, s25, 0
	ds_read_b128 v[168:171], v133
	ds_read_b128 v[172:175], v133 offset:1024
	ds_read_b128 v[176:179], v133 offset:2048
	ds_read_b128 v[180:183], v133 offset:3072
	ds_read_b128 v[184:187], v133 offset:4096
	ds_read_b128 v[188:191], v133 offset:5120
	ds_read_b128 v[198:201], v133 offset:6144
	ds_read_b128 v[202:205], v133 offset:7168
	s_add_u32 s12, s60, 0x188080
	s_addc_u32 s13, s61, 0
	s_mov_b32 s60, m0
	s_mov_b32 m0, s79
	s_nop 0
	global_load_lds_dwordx4 v130, s[12:13]
	s_mov_b32 m0, s60
	s_nop 0
	s_mov_b32 s60, m0
	s_mov_b32 m0, s96
	s_nop 0
	global_load_lds_dwordx4 v131, s[12:13]
	s_mov_b32 m0, s60
	s_waitcnt vmcnt(8)
	s_waitcnt lgkmcnt(0)
	s_barrier
	s_setprio 1
	v_mfma_scale_f32_16x16x128_f8f6f4 v[124:127], v[136:143], v[168:175], v[124:127], v219, v218 op_sel_hi:[0,0,0]
	v_mfma_scale_f32_16x16x128_f8f6f4 v[120:123], v[144:151], v[168:175], v[120:123], v219, v218 op_sel_hi:[0,0,0]
	v_mfma_scale_f32_16x16x128_f8f6f4 v[112:115], v[136:143], v[176:183], v[112:115], v219, v218 op_sel_hi:[0,0,0]
	v_mfma_scale_f32_16x16x128_f8f6f4 v[104:107], v[144:151], v[176:183], v[104:107], v219, v218 op_sel_hi:[0,0,0]
	v_mfma_scale_f32_16x16x128_f8f6f4 v[96:99], v[136:143], v[184:191], v[96:99], v219, v218 op_sel_hi:[0,0,0]
	v_mfma_scale_f32_16x16x128_f8f6f4 v[194:197], v[144:151], v[184:191], v[88:91], v219, v218 op_sel_hi:[0,0,0]
	v_mfma_scale_f32_16x16x128_f8f6f4 v[206:209], v[136:143], v[198:205], v[80:83], v219, v218 op_sel_hi:[0,0,0]
	v_mfma_scale_f32_16x16x128_f8f6f4 v[210:213], v[144:151], v[198:205], v[72:75], v219, v218 op_sel_hi:[0,0,0]
	v_mfma_scale_f32_16x16x128_f8f6f4 v[116:119], v[152:159], v[168:175], v[116:119], v219, v218 op_sel_hi:[0,0,0]
	v_mfma_scale_f32_16x16x128_f8f6f4 v[108:111], v[160:167], v[168:175], v[108:111], v219, v218 op_sel_hi:[0,0,0]
	v_mfma_scale_f32_16x16x128_f8f6f4 v[100:103], v[152:159], v[176:183], v[100:103], v219, v218 op_sel_hi:[0,0,0]
	v_mfma_scale_f32_16x16x128_f8f6f4 v[168:171], v[160:167], v[176:183], v[92:95], v219, v218 op_sel_hi:[0,0,0]
	v_mfma_scale_f32_16x16x128_f8f6f4 v[172:175], v[152:159], v[184:191], v[84:87], v219, v218 op_sel_hi:[0,0,0]
	v_mfma_scale_f32_16x16x128_f8f6f4 v[176:179], v[160:167], v[184:191], v[76:79], v219, v218 op_sel_hi:[0,0,0]
	v_mfma_scale_f32_16x16x128_f8f6f4 v[180:183], v[152:159], v[198:205], v[68:71], v219, v218 op_sel_hi:[0,0,0]
	v_mfma_scale_f32_16x16x128_f8f6f4 v[184:187], v[160:167], v[198:205], v[64:67], v219, v218 op_sel_hi:[0,0,0]
	s_setprio 0
	s_barrier
	s_nop 4
	ds_read_b128 v[64:67], v133 offset:16384
	ds_read_b128 v[68:71], v133 offset:17408
	ds_read_b128 v[72:75], v133 offset:18432
	ds_read_b128 v[76:79], v133 offset:19456
	ds_read_b128 v[80:83], v133 offset:20480
	ds_read_b128 v[84:87], v133 offset:21504
	ds_read_b128 v[88:91], v133 offset:22528
	ds_read_b128 v[92:95], v133 offset:23552
	s_mov_b32 s12, m0
	s_mov_b32 m0, s4
	s_nop 0
	global_load_lds_dwordx4 v130, s[56:57]
	s_mov_b32 m0, s12
	s_nop 0
	s_mov_b32 s12, m0
	s_mov_b32 m0, s5
	s_nop 0
	global_load_lds_dwordx4 v131, s[56:57]
	s_mov_b32 m0, s12
	s_add_u32 s12, s56, 0x188000
	s_addc_u32 s13, s57, 0
	s_mov_b32 s60, m0
	s_mov_b32 m0, s6
	s_nop 0
	global_load_lds_dwordx4 v130, s[12:13]
	s_mov_b32 m0, s60
	s_nop 0
	s_mov_b32 s60, m0
	s_mov_b32 m0, s7
	s_nop 0
	global_load_lds_dwordx4 v131, s[12:13]
	s_mov_b32 m0, s60
	s_mov_b32 s12, m0
	s_mov_b32 m0, s0
	s_nop 0
	global_load_lds_dwordx4 v130, s[24:25]
	s_mov_b32 m0, s12
	s_nop 0
	s_mov_b32 s12, m0
	s_mov_b32 m0, s44
	s_nop 0
	global_load_lds_dwordx4 v131, s[24:25]
	s_mov_b32 m0, s12
	s_waitcnt vmcnt(8)
	s_waitcnt lgkmcnt(0)
	s_barrier
	s_setprio 1
	v_mfma_scale_f32_16x16x128_f8f6f4 v[60:63], v[136:143], v[64:71], v[60:63], v219, v218 op_sel_hi:[0,0,0]
	v_mfma_scale_f32_16x16x128_f8f6f4 v[56:59], v[144:151], v[64:71], v[56:59], v219, v218 op_sel_hi:[0,0,0]
	v_mfma_scale_f32_16x16x128_f8f6f4 v[52:55], v[136:143], v[72:79], v[52:55], v219, v218 op_sel_hi:[0,0,0]
	v_mfma_scale_f32_16x16x128_f8f6f4 v[188:191], v[144:151], v[72:79], v[40:43], v219, v218 op_sel_hi:[0,0,0]
	v_mfma_scale_f32_16x16x128_f8f6f4 v[198:201], v[136:143], v[80:87], v[36:39], v219, v218 op_sel_hi:[0,0,0]
	v_mfma_scale_f32_16x16x128_f8f6f4 v[202:205], v[144:151], v[80:87], v[24:27], v219, v218 op_sel_hi:[0,0,0]
	v_mfma_scale_f32_16x16x128_f8f6f4 v[214:217], v[136:143], v[88:95], v[20:23], v219, v218 op_sel_hi:[0,0,0]
	v_mfma_scale_f32_16x16x128_f8f6f4 v[220:223], v[144:151], v[88:95], v[8:11], v219, v218 op_sel_hi:[0,0,0]
	v_mfma_scale_f32_16x16x128_f8f6f4 v[48:51], v[152:159], v[64:71], v[48:51], v219, v218 op_sel_hi:[0,0,0]
	v_mfma_scale_f32_16x16x128_f8f6f4 v[224:227], v[160:167], v[64:71], v[44:47], v219, v218 op_sel_hi:[0,0,0]
	v_mfma_scale_f32_16x16x128_f8f6f4 v[228:231], v[152:159], v[72:79], v[32:35], v219, v218 op_sel_hi:[0,0,0]
	v_mfma_scale_f32_16x16x128_f8f6f4 v[232:235], v[160:167], v[72:79], v[28:31], v219, v218 op_sel_hi:[0,0,0]
	v_mfma_scale_f32_16x16x128_f8f6f4 v[236:239], v[152:159], v[80:87], v[16:19], v219, v218 op_sel_hi:[0,0,0]
	v_mfma_scale_f32_16x16x128_f8f6f4 v[240:243], v[160:167], v[80:87], v[12:15], v219, v218 op_sel_hi:[0,0,0]
	v_mfma_scale_f32_16x16x128_f8f6f4 v[244:247], v[152:159], v[88:95], v[4:7], v219, v218 op_sel_hi:[0,0,0]
	v_mfma_scale_f32_16x16x128_f8f6f4 v[248:251], v[160:167], v[88:95], v[0:3], v219, v218 op_sel_hi:[0,0,0]
	s_setprio 0
	s_barrier
	s_nop 4
	ds_read_b128 v[0:3], v134
	ds_read_b128 v[4:7], v134 offset:1024
	ds_read_b128 v[8:11], v134 offset:2048
	ds_read_b128 v[12:15], v134 offset:3072
	ds_read_b128 v[136:139], v135
	ds_read_b128 v[140:143], v135 offset:1024
	ds_read_b128 v[144:147], v135 offset:2048
	ds_read_b128 v[148:151], v135 offset:3072
	ds_read_b128 v[16:19], v133 offset:32768
	ds_read_b128 v[20:23], v133 offset:33792
	ds_read_b128 v[24:27], v133 offset:34816
	ds_read_b128 v[28:31], v133 offset:35840
	ds_read_b128 v[32:35], v133 offset:36864
	ds_read_b128 v[36:39], v133 offset:37888
	ds_read_b128 v[40:43], v133 offset:38912
	ds_read_b128 v[44:47], v133 offset:39936
	s_add_u32 s12, s24, 0x188000
	s_addc_u32 s13, s25, 0
	s_mov_b32 s24, m0
	s_mov_b32 m0, s45
	s_nop 0
	global_load_lds_dwordx4 v130, s[12:13]
	s_mov_b32 m0, s24
	s_nop 0
	s_mov_b32 s24, m0
	s_mov_b32 m0, s58
	s_nop 0
	global_load_lds_dwordx4 v131, s[12:13]
	s_mov_b32 m0, s24
	s_waitcnt vmcnt(8)
	s_waitcnt lgkmcnt(0)
	s_barrier
	s_setprio 1
	v_mfma_scale_f32_16x16x128_f8f6f4 v[124:127], v[0:7], v[16:23], v[124:127], v219, v218 op_sel_hi:[0,0,0]
	v_mfma_scale_f32_16x16x128_f8f6f4 v[120:123], v[8:15], v[16:23], v[120:123], v219, v218 op_sel_hi:[0,0,0]
	v_mfma_scale_f32_16x16x128_f8f6f4 v[112:115], v[0:7], v[24:31], v[112:115], v219, v218 op_sel_hi:[0,0,0]
	v_mfma_scale_f32_16x16x128_f8f6f4 v[104:107], v[8:15], v[24:31], v[104:107], v219, v218 op_sel_hi:[0,0,0]
	v_mfma_scale_f32_16x16x128_f8f6f4 v[96:99], v[0:7], v[32:39], v[96:99], v219, v218 op_sel_hi:[0,0,0]
	v_mfma_scale_f32_16x16x128_f8f6f4 v[88:91], v[8:15], v[32:39], v[194:197], v219, v218 op_sel_hi:[0,0,0]
	v_mfma_scale_f32_16x16x128_f8f6f4 v[80:83], v[0:7], v[40:47], v[206:209], v219, v218 op_sel_hi:[0,0,0]
	v_mfma_scale_f32_16x16x128_f8f6f4 v[72:75], v[8:15], v[40:47], v[210:213], v219, v218 op_sel_hi:[0,0,0]
	v_mfma_scale_f32_16x16x128_f8f6f4 v[116:119], v[136:143], v[16:23], v[116:119], v219, v218 op_sel_hi:[0,0,0]
	v_mfma_scale_f32_16x16x128_f8f6f4 v[108:111], v[144:151], v[16:23], v[108:111], v219, v218 op_sel_hi:[0,0,0]
	v_mfma_scale_f32_16x16x128_f8f6f4 v[100:103], v[136:143], v[24:31], v[100:103], v219, v218 op_sel_hi:[0,0,0]
	v_mfma_scale_f32_16x16x128_f8f6f4 v[92:95], v[144:151], v[24:31], v[168:171], v219, v218 op_sel_hi:[0,0,0]
	v_mfma_scale_f32_16x16x128_f8f6f4 v[84:87], v[136:143], v[32:39], v[172:175], v219, v218 op_sel_hi:[0,0,0]
	v_mfma_scale_f32_16x16x128_f8f6f4 v[76:79], v[144:151], v[32:39], v[176:179], v219, v218 op_sel_hi:[0,0,0]
	v_mfma_scale_f32_16x16x128_f8f6f4 v[68:71], v[136:143], v[40:47], v[180:183], v219, v218 op_sel_hi:[0,0,0]
	v_mfma_scale_f32_16x16x128_f8f6f4 v[64:67], v[144:151], v[40:47], v[184:187], v219, v218 op_sel_hi:[0,0,0]
	s_setprio 0
	s_barrier
	ds_read_b128 v[28:31], v133 offset:49152
	ds_read_b128 v[32:35], v133 offset:50176
	ds_read_b128 v[152:155], v133 offset:51200
	ds_read_b128 v[156:159], v133 offset:52224
	ds_read_b128 v[160:163], v133 offset:53248
	ds_read_b128 v[164:167], v133 offset:54272
	ds_read_b128 v[168:171], v133 offset:55296
	ds_read_b128 v[172:175], v133 offset:56320
	s_add_u32 s12, s56, 0x80
	s_addc_u32 s13, s57, 0
	s_mov_b32 s24, m0
	s_mov_b32 m0, s73
	s_nop 0
	global_load_lds_dwordx4 v130, s[12:13]
	s_mov_b32 m0, s24
	s_nop 0
	s_mov_b32 s24, m0
	s_mov_b32 m0, s74
	s_nop 0
	global_load_lds_dwordx4 v131, s[12:13]
	s_mov_b32 m0, s24
	s_add_u32 s12, s56, 0x188080
	s_addc_u32 s13, s57, 0
	s_mov_b32 s24, m0
	s_mov_b32 m0, s77
	s_nop 0
	global_load_lds_dwordx4 v130, s[12:13]
	s_mov_b32 m0, s24
	s_nop 0
	s_mov_b32 s24, m0
	s_mov_b32 m0, s78
	s_nop 0
	global_load_lds_dwordx4 v131, s[12:13]
	s_mov_b32 m0, s24
	s_mov_b32 s12, m0
	s_mov_b32 m0, s75
	s_nop 0
	global_load_lds_dwordx4 v130, s[52:53]
	s_mov_b32 m0, s12
	s_nop 0
	s_mov_b32 s12, m0
	s_mov_b32 m0, s76
	s_nop 0
	global_load_lds_dwordx4 v131, s[52:53]
	s_mov_b32 m0, s12
	s_waitcnt vmcnt(8)
	s_waitcnt lgkmcnt(0)
	s_barrier
	s_setprio 1
	v_mfma_scale_f32_16x16x128_f8f6f4 v[60:63], v[0:7], v[28:35], v[60:63], v219, v218 op_sel_hi:[0,0,0]
	v_mfma_scale_f32_16x16x128_f8f6f4 v[56:59], v[8:15], v[28:35], v[56:59], v219, v218 op_sel_hi:[0,0,0]
	v_mfma_scale_f32_16x16x128_f8f6f4 v[52:55], v[0:7], v[152:159], v[52:55], v219, v218 op_sel_hi:[0,0,0]
	v_mfma_scale_f32_16x16x128_f8f6f4 v[40:43], v[8:15], v[152:159], v[188:191], v219, v218 op_sel_hi:[0,0,0]
	v_mfma_scale_f32_16x16x128_f8f6f4 v[36:39], v[0:7], v[160:167], v[198:201], v219, v218 op_sel_hi:[0,0,0]
	v_mfma_scale_f32_16x16x128_f8f6f4 v[24:27], v[8:15], v[160:167], v[202:205], v219, v218 op_sel_hi:[0,0,0]
	v_mfma_scale_f32_16x16x128_f8f6f4 v[20:23], v[0:7], v[168:175], v[214:217], v219, v218 op_sel_hi:[0,0,0]
	v_mfma_scale_f32_16x16x128_f8f6f4 v[8:11], v[8:15], v[168:175], v[220:223], v219, v218 op_sel_hi:[0,0,0]
	v_mfma_scale_f32_16x16x128_f8f6f4 v[48:51], v[136:143], v[28:35], v[48:51], v219, v218 op_sel_hi:[0,0,0]
	v_mfma_scale_f32_16x16x128_f8f6f4 v[44:47], v[144:151], v[28:35], v[224:227], v219, v218 op_sel_hi:[0,0,0]
	v_mfma_scale_f32_16x16x128_f8f6f4 v[32:35], v[136:143], v[152:159], v[228:231], v219, v218 op_sel_hi:[0,0,0]
	v_mfma_scale_f32_16x16x128_f8f6f4 v[28:31], v[144:151], v[152:159], v[232:235], v219, v218 op_sel_hi:[0,0,0]
	v_mfma_scale_f32_16x16x128_f8f6f4 v[16:19], v[136:143], v[160:167], v[236:239], v219, v218 op_sel_hi:[0,0,0]
	v_mfma_scale_f32_16x16x128_f8f6f4 v[12:15], v[144:151], v[160:167], v[240:243], v219, v218 op_sel_hi:[0,0,0]
	v_mfma_scale_f32_16x16x128_f8f6f4 v[4:7], v[136:143], v[168:175], v[244:247], v219, v218 op_sel_hi:[0,0,0]
	v_mfma_scale_f32_16x16x128_f8f6f4 v[0:3], v[144:151], v[168:175], v[248:251], v219, v218 op_sel_hi:[0,0,0]
	s_setprio 0
	s_barrier
	s_add_i32 s90, s90, 2
	s_add_u32 s62, s62, 0x100
	s_addc_u32 s63, s63, 0
	s_cmpk_lt_u32 s90, 0x60
	s_mov_b64 s[60:61], s[50:51]
	s_cbranch_scc1 .LBB0_617
	v_readlane_b32 s90, v255, 19
	v_readlane_b32 s94, v255, 21
	s_andn2_b64 vcc, exec, s[42:43]
	v_readlane_b32 s91, v255, 20
	v_readlane_b32 s95, v255, 22
	s_cbranch_vccnz .LBB0_620
	s_barrier
